# stack + cross-attention unit: V^T half-1 DMA left in flight over the first PV half (drop hipcc's vmcnt(0) at the barrier), second-half wait counts the 8 newer stores
# baseline (speedup 1.0000x reference)
.LBB0_812:
	s_or_b64 exec, exec, s[2:3]
	s_and_b64 vcc, exec, s[50:51]
	s_barrier
	s_cbranch_vccnz .LBB0_814
	s_mov_b32 s2, s87
	s_ashr_i32 s3, s2, 31
	s_lshl_b64 s[2:3], s[2:3], 3
	s_add_u32 s2, s0, s2
	s_addc_u32 s3, s1, s3
	s_mov_b64 s[2:3], s[100:101]
	s_mov_b32 s4, s87
	s_mov_b32 s6, s87
	v_mov_b32_e32 v145, v0
	s_waitcnt lgkmcnt(0)
	s_add_u32 s8, s2, s81
	s_addc_u32 s16, s3, 0
	s_ashr_i32 s5, s4, 31
	s_lshl_b64 s[2:3], s[4:5], 3
	s_add_u32 s2, s0, s2
	s_addc_u32 s3, s1, s3
	s_mov_b64 s[2:3], s[100:101]
	s_mov_b32 s5, s87
	s_mov_b32 s4, s87
	s_waitcnt lgkmcnt(0)
	s_add_u32 s2, s2, s84
	s_addc_u32 s3, s3, 0
	s_add_u32 s17, s2, 0x200000
	s_addc_u32 s18, s3, 0
	s_ashr_i32 s5, s4, 31
	s_lshl_b64 s[2:3], s[4:5], 3
	s_add_u32 s2, s0, s2
	s_addc_u32 s3, s1, s3
	s_load_dwordx2 s[2:3], s[2:3], 0xd0
	v_mov_b32_e32 v143, v4
	s_waitcnt lgkmcnt(0)
	s_add_u32 s2, s2, s80
	s_addc_u32 s3, s3, 0
	s_lshl_b32 s4, s46, 19
	s_add_u32 s2, s2, s4
	s_addc_u32 s3, s3, 0
	v_readlane_b32 s4, v253, 62
	v_readlane_b32 s5, v253, 63
	s_add_u32 s2, s2, s4
	s_addc_u32 s3, s3, s5
	s_add_u32 s4, s2, 0xe00000
	s_addc_u32 s5, s3, 0
	s_ashr_i32 s7, s6, 31
	s_lshl_b64 s[2:3], s[6:7], 3
	s_add_u32 s2, s0, s2
	s_addc_u32 s3, s1, s3
	s_mov_b64 s[2:3], s[100:101]
	s_waitcnt lgkmcnt(0)
	s_add_u32 s2, s2, s81
	v_readfirstlane_b32 s6, v145
	s_addc_u32 s3, s3, 0
	s_ashr_i32 s9, s6, 6
	s_lshl_b32 s10, s9, 5
	s_lshl_b64 s[6:7], s[74:75], 8
	s_ashr_i32 s11, s10, 31
	s_add_u32 s19, s6, s10
	s_addc_u32 s20, s7, s11
	s_lshl_b32 s6, s78, 2
	s_ashr_i32 s7, s6, 31
	s_lshl_b64 s[10:11], s[6:7], 14
	s_add_u32 s10, s17, s10
	s_addc_u32 s11, s18, s11
	s_or_b32 s12, s6, 1
	s_ashr_i32 s13, s12, 31
	s_lshl_b64 s[12:13], s[12:13], 14
	s_add_u32 s12, s17, s12
	s_addc_u32 s13, s18, s13
	s_or_b32 s14, s6, 2
	s_ashr_i32 s15, s14, 31
	s_lshl_b64 s[14:15], s[14:15], 14
	s_add_u32 s14, s17, s14
	s_addc_u32 s15, s18, s15
	s_or_b32 s6, s6, 3
	v_and_b32_e32 v144, 15, v145
	s_ashr_i32 s7, s6, 31
	s_lshl_b64 s[6:7], s[6:7], 14
	v_or_b32_e32 v6, s19, v144
	s_add_u32 s6, s17, s6
	v_mov_b32_e32 v5, v6
	s_addc_u32 s7, s18, s7
	v_ashrrev_i64 v[2:3], 30, v[4:5]
	v_mov_b32_e32 v7, s20
	v_lshl_add_u64 v[8:9], s[10:11], 0, v[2:3]
	v_lshl_add_u64 v[10:11], s[12:13], 0, v[2:3]
	v_lshl_add_u64 v[12:13], s[14:15], 0, v[2:3]
	v_lshl_add_u64 v[2:3], s[6:7], 0, v[2:3]
	global_load_dword v14, v[8:9], off
	global_load_dword v16, v[10:11], off
	global_load_dword v15, v[12:13], off
	global_load_dword v17, v[2:3], off
	v_lshlrev_b64 v[2:3], 11, v[6:7]
	v_or_b32_e32 v6, 16, v6
	v_mov_b32_e32 v5, v6
	v_ashrrev_i64 v[8:9], 30, v[4:5]
	v_lshl_add_u64 v[10:11], s[10:11], 0, v[8:9]
	v_lshl_add_u64 v[12:13], s[12:13], 0, v[8:9]
	v_lshl_add_u64 v[18:19], s[14:15], 0, v[8:9]
	v_lshl_add_u64 v[8:9], s[6:7], 0, v[8:9]
	s_lshl_b32 s6, s78, 8
	s_ashr_i32 s7, s6, 31
	s_lshl_b64 s[6:7], s[6:7], 1
	s_add_u32 s10, s8, s6
	s_addc_u32 s11, s16, s7
	v_and_b32_e32 v142, 48, v145
	global_load_dword v20, v[10:11], off
	global_load_dword v22, v[12:13], off
	global_load_dword v21, v[18:19], off
	global_load_dword v23, v[8:9], off
	v_lshl_add_u64 v[8:9], s[10:11], 0, v[142:143]
	s_mov_b64 s[10:11], 0x9e00000
	v_lshl_add_u64 v[8:9], v[8:9], 0, s[10:11]
	v_lshlrev_b64 v[6:7], 11, v[6:7]
	v_lshl_add_u64 v[10:11], v[8:9], 0, v[2:3]
	v_lshl_add_u64 v[6:7], v[8:9], 0, v[6:7]
	global_load_dwordx4 v[66:69], v[10:11], off
	global_load_dwordx4 v[62:65], v[10:11], off offset:64
	global_load_dwordx4 v[58:61], v[10:11], off offset:128
	global_load_dwordx4 v[54:57], v[10:11], off offset:192
	global_load_dwordx4 v[50:53], v[10:11], off offset:256
	global_load_dwordx4 v[46:49], v[10:11], off offset:320
	global_load_dwordx4 v[42:45], v[10:11], off offset:384
	global_load_dwordx4 v[38:41], v[10:11], off offset:448
	global_load_dwordx4 v[98:101], v[6:7], off
	global_load_dwordx4 v[94:97], v[6:7], off offset:64
	global_load_dwordx4 v[90:93], v[6:7], off offset:128
	global_load_dwordx4 v[86:89], v[6:7], off offset:192
	global_load_dwordx4 v[82:85], v[6:7], off offset:256
	global_load_dwordx4 v[78:81], v[6:7], off offset:320
	global_load_dwordx4 v[74:77], v[6:7], off offset:384
	global_load_dwordx4 v[70:73], v[6:7], off offset:448
	v_bfe_u32 v5, v145, 4, 2
	v_bitop3_b32 v6, v5, v145, 15 bitop3:0x78
	v_bitop3_b32 v8, v5, v144, 8 bitop3:0x36
	v_bitop3_b32 v30, v5, v144, 24 bitop3:0x36
	v_lshl_add_u32 v134, v144, 9, 0
	v_bitop3_b32 v7, v5, v144, 4 bitop3:0x36
	v_bitop3_b32 v9, v5, v144, 12 bitop3:0x36
	v_lshlrev_b32_e32 v149, 4, v6
	v_lshlrev_b32_e32 v136, 4, v8
	v_lshlrev_b32_e32 v152, 4, v30
	v_lshlrev_b32_e32 v137, 4, v7
	v_lshlrev_b32_e32 v135, 4, v9
	v_add_u32_e32 v170, v134, v149
	v_add_u32_e32 v172, v134, v136
	v_add_u32_e32 v176, v134, v152
	v_add_u32_e32 v171, v134, v137
	v_add_u32_e32 v173, v134, v135
	s_waitcnt vmcnt(0)
	s_barrier
	ds_read_b128 v[6:9], v170
	ds_read_b128 v[10:13], v171
	v_lshrrev_b32_e32 v146, 1, v145
	s_lshl_b32 s8, s9, 3
	s_waitcnt vmcnt(20)
	v_pk_add_f32 v[14:15], v[14:15], v[16:17]
	s_nop 0
	v_add_f32_e32 v14, v14, v15
	v_fmamk_f32 v14, v14, 0x3b800000, v236
	v_rsq_f32_e32 v148, v14
	s_waitcnt vmcnt(16)
	v_pk_add_f32 v[16:17], v[20:21], v[22:23]
	v_bitop3_b32 v22, v5, v144, 16 bitop3:0x36
	v_lshlrev_b32_e32 v150, 4, v22
	v_bitop3_b32 v22, v5, v144, 20 bitop3:0x36
	v_bitop3_b32 v5, v5, v144, 28 bitop3:0x36
	v_add_f32_e32 v15, v16, v17
	v_add_u32_e32 v174, v134, v150
	v_lshlrev_b32_e32 v151, 4, v22
	v_lshlrev_b32_e32 v153, 4, v5
	v_fmamk_f32 v102, v15, 0x3b800000, v236
	ds_read_b128 v[14:17], v172
	ds_read_b128 v[18:21], v173
	v_add_u32_e32 v175, v134, v151
	ds_read_b128 v[22:25], v174
	ds_read_b128 v[26:29], v175
	v_add_u32_e32 v177, v134, v153
	ds_read_b128 v[30:33], v176
	ds_read_b128 v[34:37], v177
	v_rsq_f32_e32 v147, v102
	v_and_b32_e32 v5, 63, v145
	s_setprio 1
	s_waitcnt vmcnt(15) lgkmcnt(7)
	v_mfma_f32_16x16x32_bf16 v[102:105], v[6:9], v[66:69], 0
	s_waitcnt vmcnt(7)
	v_mfma_f32_16x16x32_bf16 v[6:9], v[6:9], v[98:101], 0
	s_waitcnt lgkmcnt(6)
	v_mfma_f32_16x16x32_bf16 v[102:105], v[10:13], v[62:65], v[102:105]
	s_waitcnt vmcnt(6)
	v_mfma_f32_16x16x32_bf16 v[6:9], v[10:13], v[94:97], v[6:9]
	s_waitcnt lgkmcnt(5)
	v_mfma_f32_16x16x32_bf16 v[10:13], v[14:17], v[58:61], v[102:105]
	s_waitcnt vmcnt(5)
	v_mfma_f32_16x16x32_bf16 v[6:9], v[14:17], v[90:93], v[6:9]
	s_waitcnt lgkmcnt(4)
	v_mfma_f32_16x16x32_bf16 v[10:13], v[18:21], v[54:57], v[10:13]
	s_waitcnt vmcnt(4)
	v_mfma_f32_16x16x32_bf16 v[6:9], v[18:21], v[86:89], v[6:9]
	s_setprio 0
	ds_read_b128 v[14:17], v170 offset:8192
	ds_read_b128 v[18:21], v171 offset:8192
	ds_read_b128 v[102:105], v172 offset:8192
	ds_read_b128 v[106:109], v173 offset:8192
	s_setprio 1
	s_waitcnt lgkmcnt(7)
	v_mfma_f32_16x16x32_bf16 v[10:13], v[22:25], v[50:53], v[10:13]
	s_waitcnt vmcnt(3)
	v_mfma_f32_16x16x32_bf16 v[6:9], v[22:25], v[82:85], v[6:9]
	s_waitcnt lgkmcnt(6)
	v_mfma_f32_16x16x32_bf16 v[10:13], v[26:29], v[46:49], v[10:13]
	s_waitcnt vmcnt(2)
	v_mfma_f32_16x16x32_bf16 v[6:9], v[26:29], v[78:81], v[6:9]
	s_waitcnt lgkmcnt(5)
	v_mfma_f32_16x16x32_bf16 v[10:13], v[30:33], v[42:45], v[10:13]
	s_waitcnt vmcnt(1)
	v_mfma_f32_16x16x32_bf16 v[6:9], v[30:33], v[74:77], v[6:9]
	s_waitcnt lgkmcnt(4)
	v_mfma_f32_16x16x32_bf16 v[10:13], v[34:37], v[38:41], v[10:13]
	s_waitcnt vmcnt(0)
	v_mfma_f32_16x16x32_bf16 v[22:25], v[34:37], v[70:73], v[6:9]
	s_setprio 0
	s_nop 2
	ds_read_b128 v[6:9], v174 offset:8192
	ds_read_b128 v[26:29], v175 offset:8192
	ds_read_b128 v[30:33], v176 offset:8192
	ds_read_b128 v[34:37], v177 offset:8192
	s_setprio 1
	s_waitcnt lgkmcnt(7)
	v_mfma_f32_16x16x32_bf16 v[110:113], v[14:17], v[66:69], 0
	v_mfma_f32_16x16x32_bf16 v[14:17], v[14:17], v[98:101], 0
	s_waitcnt lgkmcnt(6)
	v_mfma_f32_16x16x32_bf16 v[110:113], v[18:21], v[62:65], v[110:113]
	v_mfma_f32_16x16x32_bf16 v[14:17], v[18:21], v[94:97], v[14:17]
	s_waitcnt lgkmcnt(5)
	v_mfma_f32_16x16x32_bf16 v[18:21], v[102:105], v[58:61], v[110:113]
	v_mfma_f32_16x16x32_bf16 v[14:17], v[102:105], v[90:93], v[14:17]
	s_waitcnt lgkmcnt(4)
	v_mfma_f32_16x16x32_bf16 v[18:21], v[106:109], v[54:57], v[18:21]
	v_mfma_f32_16x16x32_bf16 v[14:17], v[106:109], v[86:89], v[14:17]
	s_setprio 0
	ds_read_b128 v[102:105], v170 offset:16384
	ds_read_b128 v[106:109], v171 offset:16384
	ds_read_b128 v[110:113], v172 offset:16384
	ds_read_b128 v[114:117], v173 offset:16384
	s_setprio 1
	s_waitcnt lgkmcnt(7)
	v_mfma_f32_16x16x32_bf16 v[18:21], v[6:9], v[50:53], v[18:21]
	v_mfma_f32_16x16x32_bf16 v[6:9], v[6:9], v[82:85], v[14:17]
	s_waitcnt lgkmcnt(6)
	v_mfma_f32_16x16x32_bf16 v[14:17], v[26:29], v[46:49], v[18:21]
	v_mfma_f32_16x16x32_bf16 v[6:9], v[26:29], v[78:81], v[6:9]
	s_waitcnt lgkmcnt(5)
	v_mfma_f32_16x16x32_bf16 v[14:17], v[30:33], v[42:45], v[14:17]
	v_mfma_f32_16x16x32_bf16 v[6:9], v[30:33], v[74:77], v[6:9]
	s_waitcnt lgkmcnt(4)
	v_mfma_f32_16x16x32_bf16 v[14:17], v[34:37], v[38:41], v[14:17]
	v_mfma_f32_16x16x32_bf16 v[26:29], v[34:37], v[70:73], v[6:9]
	s_setprio 0
	s_nop 3
	ds_read_b128 v[6:9], v174 offset:16384
	ds_read_b128 v[18:21], v175 offset:16384
	ds_read_b128 v[30:33], v176 offset:16384
	ds_read_b128 v[34:37], v177 offset:16384
	s_setprio 1
	s_waitcnt lgkmcnt(7)
	v_mfma_f32_16x16x32_bf16 v[118:121], v[102:105], v[66:69], 0
	v_mfma_f32_16x16x32_bf16 v[102:105], v[102:105], v[98:101], 0
	s_waitcnt lgkmcnt(6)
	v_mfma_f32_16x16x32_bf16 v[118:121], v[106:109], v[62:65], v[118:121]
	v_mfma_f32_16x16x32_bf16 v[102:105], v[106:109], v[94:97], v[102:105]
	s_waitcnt lgkmcnt(5)
	v_mfma_f32_16x16x32_bf16 v[106:109], v[110:113], v[58:61], v[118:121]
	v_mfma_f32_16x16x32_bf16 v[102:105], v[110:113], v[90:93], v[102:105]
	s_waitcnt lgkmcnt(4)
	v_mfma_f32_16x16x32_bf16 v[106:109], v[114:117], v[54:57], v[106:109]
	v_mfma_f32_16x16x32_bf16 v[102:105], v[114:117], v[86:89], v[102:105]
	s_setprio 0
	ds_read_b128 v[110:113], v170 offset:24576
	ds_read_b128 v[114:117], v171 offset:24576
	ds_read_b128 v[118:121], v172 offset:24576
	ds_read_b128 v[122:125], v173 offset:24576
	s_setprio 1
	s_waitcnt lgkmcnt(7)
	v_mfma_f32_16x16x32_bf16 v[106:109], v[6:9], v[50:53], v[106:109]
	v_mfma_f32_16x16x32_bf16 v[6:9], v[6:9], v[82:85], v[102:105]
	s_waitcnt lgkmcnt(6)
	v_mfma_f32_16x16x32_bf16 v[102:105], v[18:21], v[46:49], v[106:109]
	v_mfma_f32_16x16x32_bf16 v[6:9], v[18:21], v[78:81], v[6:9]
	s_waitcnt lgkmcnt(5)
	v_mfma_f32_16x16x32_bf16 v[18:21], v[30:33], v[42:45], v[102:105]
	v_mfma_f32_16x16x32_bf16 v[6:9], v[30:33], v[74:77], v[6:9]
	s_waitcnt lgkmcnt(4)
	v_mfma_f32_16x16x32_bf16 v[18:21], v[34:37], v[38:41], v[18:21]
	v_mfma_f32_16x16x32_bf16 v[30:33], v[34:37], v[70:73], v[6:9]
	s_setprio 0
	s_nop 3
	ds_read_b128 v[6:9], v174 offset:24576
	ds_read_b128 v[34:37], v175 offset:24576
	ds_read_b128 v[102:105], v176 offset:24576
	ds_read_b128 v[106:109], v177 offset:24576
	s_setprio 1
	s_waitcnt lgkmcnt(7)
	v_mfma_f32_16x16x32_bf16 v[126:129], v[110:113], v[66:69], 0
	v_mfma_f32_16x16x32_bf16 v[110:113], v[110:113], v[98:101], 0
	s_waitcnt lgkmcnt(6)
	v_mfma_f32_16x16x32_bf16 v[126:129], v[114:117], v[62:65], v[126:129]
	v_mfma_f32_16x16x32_bf16 v[110:113], v[114:117], v[94:97], v[110:113]
	s_waitcnt lgkmcnt(5)
	v_mfma_f32_16x16x32_bf16 v[114:117], v[118:121], v[58:61], v[126:129]
	v_mfma_f32_16x16x32_bf16 v[110:113], v[118:121], v[90:93], v[110:113]
	s_waitcnt lgkmcnt(4)
	v_mfma_f32_16x16x32_bf16 v[114:117], v[122:125], v[54:57], v[114:117]
	v_mfma_f32_16x16x32_bf16 v[110:113], v[122:125], v[86:89], v[110:113]
	s_setprio 0
	ds_read_b128 v[118:121], v170 offset:32768
	ds_read_b128 v[122:125], v171 offset:32768
	ds_read_b128 v[126:129], v172 offset:32768
	ds_read_b128 v[130:133], v173 offset:32768
	s_setprio 1
	s_waitcnt lgkmcnt(7)
	v_mfma_f32_16x16x32_bf16 v[114:117], v[6:9], v[50:53], v[114:117]
	v_mfma_f32_16x16x32_bf16 v[6:9], v[6:9], v[82:85], v[110:113]
	s_waitcnt lgkmcnt(6)
	v_mfma_f32_16x16x32_bf16 v[110:113], v[34:37], v[46:49], v[114:117]
	v_mfma_f32_16x16x32_bf16 v[6:9], v[34:37], v[78:81], v[6:9]
	s_waitcnt lgkmcnt(5)
	v_mfma_f32_16x16x32_bf16 v[34:37], v[102:105], v[42:45], v[110:113]
	v_mfma_f32_16x16x32_bf16 v[6:9], v[102:105], v[74:77], v[6:9]
	s_waitcnt lgkmcnt(4)
	v_mfma_f32_16x16x32_bf16 v[114:117], v[106:109], v[38:41], v[34:37]
	v_mfma_f32_16x16x32_bf16 v[34:37], v[106:109], v[70:73], v[6:9]
	s_setprio 0
	s_nop 3
	ds_read_b128 v[6:9], v174 offset:32768
	ds_read_b128 v[102:105], v175 offset:32768
	ds_read_b128 v[106:109], v176 offset:32768
	ds_read_b128 v[110:113], v177 offset:32768
	s_setprio 1
	s_waitcnt lgkmcnt(7)
	v_mfma_f32_16x16x32_bf16 v[138:141], v[118:121], v[66:69], 0
	v_mfma_f32_16x16x32_bf16 v[118:121], v[118:121], v[98:101], 0
	s_waitcnt lgkmcnt(6)
	v_mfma_f32_16x16x32_bf16 v[138:141], v[122:125], v[62:65], v[138:141]
	v_mfma_f32_16x16x32_bf16 v[118:121], v[122:125], v[94:97], v[118:121]
	s_waitcnt lgkmcnt(5)
	v_mfma_f32_16x16x32_bf16 v[122:125], v[126:129], v[58:61], v[138:141]
	v_mfma_f32_16x16x32_bf16 v[118:121], v[126:129], v[90:93], v[118:121]
	s_waitcnt lgkmcnt(4)
	v_mfma_f32_16x16x32_bf16 v[122:125], v[130:133], v[54:57], v[122:125]
	v_mfma_f32_16x16x32_bf16 v[118:121], v[130:133], v[86:89], v[118:121]
	s_setprio 0
	ds_read_b128 v[126:129], v170 offset:40960
	ds_read_b128 v[130:133], v171 offset:40960
	ds_read_b128 v[138:141], v172 offset:40960
	ds_read_b128 v[154:157], v173 offset:40960
	s_setprio 1
	s_waitcnt lgkmcnt(7)
	v_mfma_f32_16x16x32_bf16 v[122:125], v[6:9], v[50:53], v[122:125]
	v_mfma_f32_16x16x32_bf16 v[6:9], v[6:9], v[82:85], v[118:121]
	s_waitcnt lgkmcnt(6)
	v_mfma_f32_16x16x32_bf16 v[118:121], v[102:105], v[46:49], v[122:125]
	v_mfma_f32_16x16x32_bf16 v[6:9], v[102:105], v[78:81], v[6:9]
	s_waitcnt lgkmcnt(5)
	v_mfma_f32_16x16x32_bf16 v[102:105], v[106:109], v[42:45], v[118:121]
	v_mfma_f32_16x16x32_bf16 v[6:9], v[106:109], v[74:77], v[6:9]
	s_waitcnt lgkmcnt(4)
	v_mfma_f32_16x16x32_bf16 v[118:121], v[110:113], v[38:41], v[102:105]
	v_mfma_f32_16x16x32_bf16 v[102:105], v[110:113], v[70:73], v[6:9]
	s_setprio 0
	s_nop 3
	ds_read_b128 v[6:9], v174 offset:40960
	ds_read_b128 v[106:109], v175 offset:40960
	ds_read_b128 v[110:113], v176 offset:40960
	ds_read_b128 v[122:125], v177 offset:40960
	s_setprio 1
	s_waitcnt lgkmcnt(7)
	v_mfma_f32_16x16x32_bf16 v[158:161], v[126:129], v[66:69], 0
	v_mfma_f32_16x16x32_bf16 v[126:129], v[126:129], v[98:101], 0
	s_waitcnt lgkmcnt(6)
	v_mfma_f32_16x16x32_bf16 v[158:161], v[130:133], v[62:65], v[158:161]
	v_mfma_f32_16x16x32_bf16 v[126:129], v[130:133], v[94:97], v[126:129]
	s_waitcnt lgkmcnt(5)
	v_mfma_f32_16x16x32_bf16 v[130:133], v[138:141], v[58:61], v[158:161]
	v_mfma_f32_16x16x32_bf16 v[126:129], v[138:141], v[90:93], v[126:129]
	s_waitcnt lgkmcnt(4)
	v_mfma_f32_16x16x32_bf16 v[130:133], v[154:157], v[54:57], v[130:133]
	v_mfma_f32_16x16x32_bf16 v[126:129], v[154:157], v[86:89], v[126:129]
	s_setprio 0
	ds_read_b128 v[138:141], v170 offset:49152
	ds_read_b128 v[154:157], v171 offset:49152
	ds_read_b128 v[158:161], v172 offset:49152
	ds_read_b128 v[162:165], v173 offset:49152
	s_setprio 1
	s_waitcnt lgkmcnt(7)
	v_mfma_f32_16x16x32_bf16 v[130:133], v[6:9], v[50:53], v[130:133]
	v_mfma_f32_16x16x32_bf16 v[6:9], v[6:9], v[82:85], v[126:129]
	s_waitcnt lgkmcnt(6)
	v_mfma_f32_16x16x32_bf16 v[126:129], v[106:109], v[46:49], v[130:133]
	v_mfma_f32_16x16x32_bf16 v[6:9], v[106:109], v[78:81], v[6:9]
	s_waitcnt lgkmcnt(5)
	v_mfma_f32_16x16x32_bf16 v[106:109], v[110:113], v[42:45], v[126:129]
	v_mfma_f32_16x16x32_bf16 v[6:9], v[110:113], v[74:77], v[6:9]
	s_waitcnt lgkmcnt(4)
	v_mfma_f32_16x16x32_bf16 v[126:129], v[122:125], v[38:41], v[106:109]
	v_mfma_f32_16x16x32_bf16 v[106:109], v[122:125], v[70:73], v[6:9]
	s_setprio 0
	s_nop 3
	ds_read_b128 v[6:9], v174 offset:49152
	ds_read_b128 v[110:113], v175 offset:49152
	ds_read_b128 v[122:125], v176 offset:49152
	ds_read_b128 v[130:133], v177 offset:49152
	s_setprio 1
	s_waitcnt lgkmcnt(7)
	v_mfma_f32_16x16x32_bf16 v[166:169], v[138:141], v[66:69], 0
	v_mfma_f32_16x16x32_bf16 v[138:141], v[138:141], v[98:101], 0
	s_waitcnt lgkmcnt(6)
	v_mfma_f32_16x16x32_bf16 v[166:169], v[154:157], v[62:65], v[166:169]
	v_mfma_f32_16x16x32_bf16 v[138:141], v[154:157], v[94:97], v[138:141]
	s_waitcnt lgkmcnt(5)
	v_mfma_f32_16x16x32_bf16 v[154:157], v[158:161], v[58:61], v[166:169]
	v_mfma_f32_16x16x32_bf16 v[138:141], v[158:161], v[90:93], v[138:141]
	s_waitcnt lgkmcnt(4)
	v_mfma_f32_16x16x32_bf16 v[154:157], v[162:165], v[54:57], v[154:157]
	v_mfma_f32_16x16x32_bf16 v[138:141], v[162:165], v[86:89], v[138:141]
	s_setprio 0
	ds_read_b128 v[158:161], v170 offset:57344
	ds_read_b128 v[162:165], v171 offset:57344
	ds_read_b128 v[166:169], v172 offset:57344
	ds_read_b128 v[170:173], v173 offset:57344
	s_setprio 1
	s_waitcnt lgkmcnt(7)
	v_mfma_f32_16x16x32_bf16 v[154:157], v[6:9], v[50:53], v[154:157]
	v_mfma_f32_16x16x32_bf16 v[6:9], v[6:9], v[82:85], v[138:141]
	s_waitcnt lgkmcnt(6)
	v_mfma_f32_16x16x32_bf16 v[138:141], v[110:113], v[46:49], v[154:157]
	v_mfma_f32_16x16x32_bf16 v[6:9], v[110:113], v[78:81], v[6:9]
	s_waitcnt lgkmcnt(5)
	v_mfma_f32_16x16x32_bf16 v[110:113], v[122:125], v[42:45], v[138:141]
	v_mfma_f32_16x16x32_bf16 v[6:9], v[122:125], v[74:77], v[6:9]
	s_waitcnt lgkmcnt(4)
	v_mfma_f32_16x16x32_bf16 v[122:125], v[130:133], v[38:41], v[110:113]
	v_mfma_f32_16x16x32_bf16 v[110:113], v[130:133], v[70:73], v[6:9]
	s_setprio 0
	s_nop 3
	ds_read_b128 v[6:9], v174 offset:57344
	ds_read_b128 v[130:133], v175 offset:57344
	ds_read_b128 v[138:141], v176 offset:57344
	ds_read_b128 v[154:157], v177 offset:57344
	s_setprio 1
	s_waitcnt lgkmcnt(7)
	v_mfma_f32_16x16x32_bf16 v[174:177], v[158:161], v[66:69], 0
	v_mfma_f32_16x16x32_bf16 v[158:161], v[158:161], v[98:101], 0
	s_waitcnt lgkmcnt(6)
	v_mfma_f32_16x16x32_bf16 v[174:177], v[162:165], v[62:65], v[174:177]
	v_mfma_f32_16x16x32_bf16 v[158:161], v[162:165], v[94:97], v[158:161]
	s_waitcnt lgkmcnt(5)
	v_mfma_f32_16x16x32_bf16 v[162:165], v[166:169], v[58:61], v[174:177]
	v_mfma_f32_16x16x32_bf16 v[158:161], v[166:169], v[90:93], v[158:161]
	s_waitcnt lgkmcnt(4)
	v_mfma_f32_16x16x32_bf16 v[162:165], v[170:173], v[54:57], v[162:165]
	v_mfma_f32_16x16x32_bf16 v[158:161], v[170:173], v[86:89], v[158:161]
	s_setprio 0
	s_setprio 1
	s_waitcnt lgkmcnt(3)
	v_mfma_f32_16x16x32_bf16 v[162:165], v[6:9], v[50:53], v[162:165]
	v_mfma_f32_16x16x32_bf16 v[6:9], v[6:9], v[82:85], v[158:161]
	s_waitcnt lgkmcnt(2)
	v_mfma_f32_16x16x32_bf16 v[158:161], v[130:133], v[46:49], v[162:165]
	v_mfma_f32_16x16x32_bf16 v[6:9], v[130:133], v[78:81], v[6:9]
	s_waitcnt lgkmcnt(1)
	v_mfma_f32_16x16x32_bf16 v[130:133], v[138:141], v[42:45], v[158:161]
	v_mfma_f32_16x16x32_bf16 v[6:9], v[138:141], v[74:77], v[6:9]
	s_waitcnt lgkmcnt(0)
	v_mfma_f32_16x16x32_bf16 v[130:133], v[154:157], v[38:41], v[130:133]
	v_mfma_f32_16x16x32_bf16 v[138:141], v[154:157], v[70:73], v[6:9]
	s_setprio 0
	s_nop 3
	v_mul_f32_e32 v7, v148, v14
	v_mul_f32_e32 v6, v148, v10
	v_exp_f32_e32 v8, v7
	v_mul_f32_e32 v7, v148, v11
	v_mul_f32_e32 v10, v148, v12
	v_mul_f32_e32 v12, v148, v13
	v_exp_f32_e32 v6, v6
	v_exp_f32_e32 v7, v7
	v_mul_f32_e32 v9, v148, v15
	v_exp_f32_e32 v10, v10
	v_mul_f32_e32 v11, v148, v16
	v_exp_f32_e32 v12, v12
	v_mul_f32_e32 v13, v148, v17
	v_exp_f32_e32 v9, v9
	v_exp_f32_e32 v11, v11
	v_exp_f32_e32 v13, v13
	v_add_f32_e32 v14, v6, v7
	v_add_f32_e32 v15, v10, v12
	v_add_f32_e32 v14, v14, v15
	v_add_f32_e32 v15, v8, v9
	v_add_f32_e32 v16, v11, v13
	v_add_f32_e32 v15, v15, v16
	v_cvt_pk_bf16_f32 v8, v8, v9
	v_cvt_pk_bf16_f32 v9, v11, v13
	v_mul_f32_e32 v11, v148, v114
	v_add_f32_e32 v14, v14, v15
	v_cvt_pk_bf16_f32 v6, v6, v7
	v_cvt_pk_bf16_f32 v7, v10, v12
	v_mul_f32_e32 v10, v148, v18
	v_exp_f32_e32 v12, v11
	v_mul_f32_e32 v11, v148, v19
	v_mul_f32_e32 v15, v148, v20
	v_mul_f32_e32 v17, v148, v21
	v_exp_f32_e32 v10, v10
	v_exp_f32_e32 v11, v11
	v_mul_f32_e32 v13, v148, v115
	v_exp_f32_e32 v15, v15
	v_mul_f32_e32 v16, v148, v116
	v_exp_f32_e32 v17, v17
	v_mul_f32_e32 v18, v148, v117
	v_exp_f32_e32 v13, v13
	v_exp_f32_e32 v16, v16
	v_exp_f32_e32 v18, v18
	v_add_f32_e32 v19, v10, v11
	v_add_f32_e32 v20, v15, v17
	v_add_f32_e32 v19, v19, v20
	v_add_f32_e32 v20, v12, v13
	v_add_f32_e32 v21, v16, v18
	v_add_f32_e32 v20, v20, v21
	v_add_f32_e32 v14, 0, v14
	v_add_f32_e32 v19, v19, v20
	v_add_f32_e32 v14, v14, v19
	v_cvt_pk_bf16_f32 v10, v10, v11
	v_cvt_pk_bf16_f32 v11, v15, v17
	v_mul_f32_e32 v15, v148, v118
	v_mul_f32_e32 v17, v148, v119
	v_mul_f32_e32 v19, v148, v120
	v_mul_f32_e32 v21, v148, v121
	v_cvt_pk_bf16_f32 v12, v12, v13
	v_cvt_pk_bf16_f32 v13, v16, v18
	v_exp_f32_e32 v15, v15
	v_mul_f32_e32 v16, v148, v126
	v_exp_f32_e32 v17, v17
	v_mul_f32_e32 v18, v148, v127
	v_exp_f32_e32 v19, v19
	v_mul_f32_e32 v20, v148, v128
	v_exp_f32_e32 v21, v21
	v_mul_f32_e32 v114, v148, v129
	v_exp_f32_e32 v16, v16
	v_exp_f32_e32 v18, v18
	v_exp_f32_e32 v20, v20
	v_exp_f32_e32 v114, v114
	v_add_f32_e32 v115, v15, v17
	v_add_f32_e32 v116, v19, v21
	v_add_f32_e32 v115, v115, v116
	v_add_f32_e32 v116, v16, v18
	v_add_f32_e32 v117, v20, v114
	v_add_f32_e32 v116, v116, v117
	v_add_f32_e32 v115, v115, v116
	v_add_f32_e32 v115, v14, v115
	v_cvt_pk_bf16_f32 v14, v15, v17
	v_cvt_pk_bf16_f32 v15, v19, v21
	v_mul_f32_e32 v19, v148, v130
	v_cvt_pk_bf16_f32 v16, v16, v18
	v_cvt_pk_bf16_f32 v17, v20, v114
	v_mul_f32_e32 v18, v148, v122
	v_exp_f32_e32 v20, v19
	v_mul_f32_e32 v19, v148, v123
	v_mul_f32_e32 v114, v148, v124
	v_mul_f32_e32 v117, v148, v125
	v_exp_f32_e32 v18, v18
	v_exp_f32_e32 v19, v19
	v_mul_f32_e32 v21, v148, v131
	v_exp_f32_e32 v114, v114
	v_mul_f32_e32 v116, v148, v132
	v_exp_f32_e32 v117, v117
	v_mul_f32_e32 v118, v148, v133
	v_exp_f32_e32 v21, v21
	v_exp_f32_e32 v116, v116
	v_exp_f32_e32 v118, v118
	v_mul_f32_e32 v22, v147, v22
	v_mul_f32_e32 v23, v147, v23
	v_mul_f32_e32 v24, v147, v24
	v_mul_f32_e32 v25, v147, v25
	v_add_f32_e32 v119, v18, v19
	v_add_f32_e32 v120, v114, v117
	v_exp_f32_e32 v22, v22
	v_mul_f32_e32 v26, v147, v26
	v_exp_f32_e32 v23, v23
	v_mul_f32_e32 v27, v147, v27
	v_exp_f32_e32 v24, v24
	v_exp_f32_e32 v25, v25
	v_add_f32_e32 v119, v119, v120
	v_add_f32_e32 v120, v20, v21
	v_add_f32_e32 v121, v116, v118
	v_exp_f32_e32 v26, v26
	v_exp_f32_e32 v27, v27
	v_mul_f32_e32 v28, v147, v28
	v_mul_f32_e32 v29, v147, v29
	v_add_f32_e32 v120, v120, v121
	v_exp_f32_e32 v28, v28
	v_exp_f32_e32 v29, v29
	v_add_f32_e32 v119, v119, v120
	v_add_f32_e32 v155, v115, v119
	v_cvt_pk_bf16_f32 v18, v18, v19
	v_cvt_pk_bf16_f32 v19, v114, v117
	v_add_f32_e32 v114, v22, v23
	v_add_f32_e32 v115, v24, v25
	v_add_f32_e32 v114, v114, v115
	v_add_f32_e32 v115, v26, v27
	v_cvt_pk_bf16_f32 v22, v22, v23
	v_cvt_pk_bf16_f32 v23, v24, v25
	v_cvt_pk_bf16_f32 v24, v26, v27
	v_mul_f32_e32 v27, v147, v34
	v_cvt_pk_bf16_f32 v20, v20, v21
	v_cvt_pk_bf16_f32 v21, v116, v118
	v_add_f32_e32 v116, v28, v29
	v_cvt_pk_bf16_f32 v25, v28, v29
	v_mul_f32_e32 v26, v147, v30
	v_exp_f32_e32 v28, v27
	v_mul_f32_e32 v27, v147, v31
	v_mul_f32_e32 v30, v147, v32
	v_mul_f32_e32 v32, v147, v33
	v_exp_f32_e32 v26, v26
	v_exp_f32_e32 v27, v27
	v_mul_f32_e32 v29, v147, v35
	v_exp_f32_e32 v30, v30
	v_mul_f32_e32 v31, v147, v36
	v_exp_f32_e32 v32, v32
	v_mul_f32_e32 v33, v147, v37
	v_exp_f32_e32 v29, v29
	v_exp_f32_e32 v31, v31
	v_exp_f32_e32 v33, v33
	v_add_f32_e32 v34, v26, v27
	v_add_f32_e32 v35, v30, v32
	v_add_f32_e32 v34, v34, v35
	v_add_f32_e32 v35, v28, v29
	v_add_f32_e32 v36, v31, v33
	v_add_f32_e32 v35, v35, v36
	v_cvt_pk_bf16_f32 v28, v28, v29
	v_cvt_pk_bf16_f32 v29, v31, v33
	v_mul_f32_e32 v31, v147, v106
	v_add_f32_e32 v34, v34, v35
	v_cvt_pk_bf16_f32 v26, v26, v27
	v_cvt_pk_bf16_f32 v27, v30, v32
	v_mul_f32_e32 v30, v147, v102
	v_exp_f32_e32 v32, v31
	v_mul_f32_e32 v31, v147, v103
	v_mul_f32_e32 v35, v147, v104
	v_mul_f32_e32 v37, v147, v105
	v_exp_f32_e32 v30, v30
	v_exp_f32_e32 v31, v31
	v_mul_f32_e32 v33, v147, v107
	v_exp_f32_e32 v35, v35
	v_mul_f32_e32 v36, v147, v108
	v_exp_f32_e32 v37, v37
	v_mul_f32_e32 v102, v147, v109
	v_exp_f32_e32 v33, v33
	v_exp_f32_e32 v36, v36
	v_exp_f32_e32 v102, v102
	v_add_f32_e32 v115, v115, v116
	v_add_f32_e32 v103, v30, v31
	v_add_f32_e32 v104, v35, v37
	v_add_f32_e32 v114, v114, v115
	v_add_f32_e32 v103, v103, v104
	v_add_f32_e32 v104, v32, v33
	v_add_f32_e32 v105, v36, v102
	v_add_f32_e32 v114, 0, v114
	v_add_f32_e32 v104, v104, v105
	v_add_f32_e32 v34, v114, v34
	v_add_f32_e32 v103, v103, v104
	v_add_f32_e32 v34, v34, v103
	v_cvt_pk_bf16_f32 v30, v30, v31
	v_cvt_pk_bf16_f32 v31, v35, v37
	v_mul_f32_e32 v35, v147, v110
	v_mul_f32_e32 v37, v147, v111
	v_mul_f32_e32 v103, v147, v112
	v_mul_f32_e32 v105, v147, v113
	v_cvt_pk_bf16_f32 v32, v32, v33
	v_cvt_pk_bf16_f32 v33, v36, v102
	v_exp_f32_e32 v35, v35
	v_mul_f32_e32 v36, v147, v138
	v_exp_f32_e32 v37, v37
	v_mul_f32_e32 v102, v147, v139
	v_exp_f32_e32 v103, v103
	v_mul_f32_e32 v104, v147, v140
	v_exp_f32_e32 v105, v105
	v_mul_f32_e32 v106, v147, v141
	v_exp_f32_e32 v36, v36
	v_exp_f32_e32 v102, v102
	v_exp_f32_e32 v104, v104
	v_exp_f32_e32 v106, v106
	v_add_f32_e32 v107, v35, v37
	v_add_f32_e32 v108, v103, v105
	v_add_f32_e32 v107, v107, v108
	v_add_f32_e32 v108, v36, v102
	v_add_f32_e32 v109, v104, v106
	v_add_f32_e32 v108, v108, v109
	v_add_f32_e32 v107, v107, v108
	v_cvt_pk_bf16_f32 v36, v36, v102
	v_mov_b32_e32 v102, v5
	v_add_f32_e32 v154, v34, v107
	v_cvt_pk_bf16_f32 v34, v35, v37
	v_cvt_pk_bf16_f32 v37, v104, v106
	s_barrier
	v_cvt_pk_bf16_f32 v35, v103, v105
	v_mov_b32_e32 v105, v4
	v_ashrrev_i32_e32 v106, 5, v102
	v_and_b32_e32 v107, 31, v102
	v_lshl_add_u32 v102, s9, 4, v106
	v_lshrrev_b32_e32 v103, 1, v102
	v_and_b32_e32 v103, 12, v103
	v_and_b32_e32 v108, 3, v106
	v_bitop3_b32 v104, v103, v107, v108 bitop3:0x36
	v_ashrrev_i32_e32 v103, 31, v102
	v_lshlrev_b64 v[102:103], 9, v[102:103]
	v_lshl_add_u64 v[102:103], s[4:5], 0, v[102:103]
	v_lshlrev_b32_e32 v104, 4, v104
	s_lshl_b32 s9, s9, 13
	v_lshl_add_u64 v[102:103], v[102:103], 0, v[104:105]
	s_add_i32 m0, s9, 0
	s_or_b32 s9, s8, 1
	global_load_lds_dwordx4 v[102:103], off
	v_lshl_add_u32 v102, s9, 1, v106
	v_lshrrev_b32_e32 v103, 1, v102
	v_and_b32_e32 v103, 12, v103
	v_and_b32_e32 v104, 3, v102
	v_bitop3_b32 v104, v103, v107, v104 bitop3:0x36
	v_ashrrev_i32_e32 v103, 31, v102
	v_lshlrev_b64 v[102:103], 9, v[102:103]
	v_lshl_add_u64 v[102:103], s[4:5], 0, v[102:103]
	v_lshlrev_b32_e32 v104, 4, v104
	s_lshl_b32 s9, s9, 10
	v_lshl_add_u64 v[102:103], v[102:103], 0, v[104:105]
	s_add_i32 m0, s9, 0
	s_or_b32 s9, s8, 2
	global_load_lds_dwordx4 v[102:103], off
	v_lshl_add_u32 v102, s9, 1, v106
	v_lshrrev_b32_e32 v103, 1, v102
	v_and_b32_e32 v103, 12, v103
	v_bitop3_b32 v104, v103, v107, v108 bitop3:0x36
	v_ashrrev_i32_e32 v103, 31, v102
	v_lshlrev_b64 v[102:103], 9, v[102:103]
	v_lshl_add_u64 v[102:103], s[4:5], 0, v[102:103]
	v_lshlrev_b32_e32 v104, 4, v104
	s_lshl_b32 s9, s9, 10
	v_lshl_add_u64 v[102:103], v[102:103], 0, v[104:105]
	s_add_i32 m0, s9, 0
	s_or_b32 s9, s8, 3
	global_load_lds_dwordx4 v[102:103], off
	v_lshl_add_u32 v102, s9, 1, v106
	v_lshrrev_b32_e32 v103, 1, v102
	v_and_b32_e32 v103, 12, v103
	v_and_b32_e32 v104, 3, v102
	v_bitop3_b32 v104, v103, v107, v104 bitop3:0x36
	v_ashrrev_i32_e32 v103, 31, v102
	v_lshlrev_b64 v[102:103], 9, v[102:103]
	v_lshl_add_u64 v[102:103], s[4:5], 0, v[102:103]
	v_lshlrev_b32_e32 v104, 4, v104
	s_lshl_b32 s9, s9, 10
	v_lshl_add_u64 v[102:103], v[102:103], 0, v[104:105]
	s_add_i32 m0, s9, 0
	s_or_b32 s9, s8, 4
	global_load_lds_dwordx4 v[102:103], off
	v_lshl_add_u32 v102, s9, 1, v106
	v_lshrrev_b32_e32 v103, 1, v102
	v_and_b32_e32 v103, 12, v103
	v_bitop3_b32 v104, v103, v107, v108 bitop3:0x36
	v_ashrrev_i32_e32 v103, 31, v102
	v_lshlrev_b64 v[102:103], 9, v[102:103]
	v_lshl_add_u64 v[102:103], s[4:5], 0, v[102:103]
	v_lshlrev_b32_e32 v104, 4, v104
	s_lshl_b32 s9, s9, 10
	v_lshl_add_u64 v[102:103], v[102:103], 0, v[104:105]
	s_add_i32 m0, s9, 0
	s_or_b32 s9, s8, 5
	global_load_lds_dwordx4 v[102:103], off
	v_lshl_add_u32 v102, s9, 1, v106
	v_lshrrev_b32_e32 v103, 1, v102
	v_and_b32_e32 v103, 12, v103
	v_and_b32_e32 v104, 3, v102
	v_bitop3_b32 v104, v103, v107, v104 bitop3:0x36
	v_ashrrev_i32_e32 v103, 31, v102
	v_lshlrev_b64 v[102:103], 9, v[102:103]
	v_lshl_add_u64 v[102:103], s[4:5], 0, v[102:103]
	v_lshlrev_b32_e32 v104, 4, v104
	s_lshl_b32 s9, s9, 10
	v_lshl_add_u64 v[102:103], v[102:103], 0, v[104:105]
	s_add_i32 m0, s9, 0
	s_or_b32 s9, s8, 6
	global_load_lds_dwordx4 v[102:103], off
	v_lshl_add_u32 v102, s9, 1, v106
	v_lshrrev_b32_e32 v103, 1, v102
	v_and_b32_e32 v103, 12, v103
	v_bitop3_b32 v104, v103, v107, v108 bitop3:0x36
	v_ashrrev_i32_e32 v103, 31, v102
	v_lshlrev_b64 v[102:103], 9, v[102:103]
	v_lshl_add_u64 v[102:103], s[4:5], 0, v[102:103]
	v_lshlrev_b32_e32 v104, 4, v104
	s_lshl_b32 s9, s9, 10
	v_lshl_add_u64 v[102:103], v[102:103], 0, v[104:105]
	s_add_i32 m0, s9, 0
	s_or_b32 s9, s8, 7
	global_load_lds_dwordx4 v[102:103], off
	v_lshl_add_u32 v102, s9, 1, v106
	v_lshrrev_b32_e32 v103, 1, v102
	v_and_b32_e32 v103, 12, v103
	v_and_b32_e32 v104, 3, v102
	v_bitop3_b32 v104, v103, v107, v104 bitop3:0x36
	v_ashrrev_i32_e32 v103, 31, v102
	v_lshlrev_b64 v[102:103], 9, v[102:103]
	v_lshl_add_u64 v[102:103], s[4:5], 0, v[102:103]
	v_lshlrev_b32_e32 v104, 4, v104
	s_lshl_b32 s9, s9, 10
	v_lshl_add_u64 v[102:103], v[102:103], 0, v[104:105]
	s_add_i32 m0, s9, 0
	v_add_u32_e32 v130, 0x10000, v134
	global_load_lds_dwordx4 v[102:103], off
	v_add_u32_e32 v102, v130, v149
	v_add_u32_e32 v106, v130, v137
	v_add_u32_e32 v110, v130, v136
	v_add_u32_e32 v114, v130, v135
	v_add_u32_e32 v118, v130, v150
	v_add_u32_e32 v122, v130, v151
	v_add_u32_e32 v126, v130, v152
	v_add_u32_e32 v130, v130, v153
	ds_read_b128 v[102:105], v102
	ds_read_b128 v[106:109], v106
	ds_read_b128 v[110:113], v110
	ds_read_b128 v[114:117], v114
	ds_read_b128 v[118:121], v118
	ds_read_b128 v[122:125], v122
	ds_read_b128 v[126:129], v126
	ds_read_b128 v[130:133], v130
	s_setprio 1
	s_waitcnt lgkmcnt(0)
	v_mfma_f32_16x16x32_bf16 v[138:141], v[102:105], v[66:69], 0
	v_mfma_f32_16x16x32_bf16 v[102:105], v[102:105], v[98:101], 0
	v_mfma_f32_16x16x32_bf16 v[138:141], v[106:109], v[62:65], v[138:141]
	v_mfma_f32_16x16x32_bf16 v[102:105], v[106:109], v[94:97], v[102:105]
	v_mfma_f32_16x16x32_bf16 v[106:109], v[110:113], v[58:61], v[138:141]
	v_mfma_f32_16x16x32_bf16 v[102:105], v[110:113], v[90:93], v[102:105]
	v_mfma_f32_16x16x32_bf16 v[106:109], v[114:117], v[54:57], v[106:109]
	v_mfma_f32_16x16x32_bf16 v[102:105], v[114:117], v[86:89], v[102:105]
	s_setprio 0
	v_add_u32_e32 v160, 0x12000, v134
	v_add_u32_e32 v110, v160, v149
	v_add_u32_e32 v114, v160, v137
	v_add_u32_e32 v138, v160, v136
	v_add_u32_e32 v156, v160, v135
	ds_read_b128 v[110:113], v110
	ds_read_b128 v[114:117], v114
	ds_read_b128 v[138:141], v138
	ds_read_b128 v[156:159], v156
	s_setprio 1
	v_mfma_f32_16x16x32_bf16 v[106:109], v[118:121], v[50:53], v[106:109]
	v_mfma_f32_16x16x32_bf16 v[102:105], v[118:121], v[82:85], v[102:105]
	v_mfma_f32_16x16x32_bf16 v[106:109], v[122:125], v[46:49], v[106:109]
	v_mfma_f32_16x16x32_bf16 v[102:105], v[122:125], v[78:81], v[102:105]
	v_mfma_f32_16x16x32_bf16 v[106:109], v[126:129], v[42:45], v[106:109]
	v_mfma_f32_16x16x32_bf16 v[102:105], v[126:129], v[74:77], v[102:105]
	v_mfma_f32_16x16x32_bf16 v[122:125], v[130:133], v[38:41], v[106:109]
	v_mfma_f32_16x16x32_bf16 v[102:105], v[130:133], v[70:73], v[102:105]
	s_setprio 0
	s_nop 3
	v_add_u32_e32 v106, v160, v150
	v_add_u32_e32 v118, v160, v151
	v_add_u32_e32 v126, v160, v152
	ds_read_b128 v[106:109], v106
	ds_read_b128 v[118:121], v118
	v_add_u32_e32 v130, v160, v153
	ds_read_b128 v[126:129], v126
	ds_read_b128 v[160:163], v130
	s_setprio 1
	s_waitcnt lgkmcnt(0)
	v_mfma_f32_16x16x32_bf16 v[130:133], v[110:113], v[66:69], 0
	v_mfma_f32_16x16x32_bf16 v[110:113], v[110:113], v[98:101], 0
	v_mfma_f32_16x16x32_bf16 v[130:133], v[114:117], v[62:65], v[130:133]
	v_mfma_f32_16x16x32_bf16 v[110:113], v[114:117], v[94:97], v[110:113]
	v_mfma_f32_16x16x32_bf16 v[114:117], v[138:141], v[58:61], v[130:133]
	v_mfma_f32_16x16x32_bf16 v[110:113], v[138:141], v[90:93], v[110:113]
	v_mfma_f32_16x16x32_bf16 v[114:117], v[156:159], v[54:57], v[114:117]
	v_mfma_f32_16x16x32_bf16 v[110:113], v[156:159], v[86:89], v[110:113]
	s_setprio 0
	v_add_u32_e32 v172, 0x14000, v134
	s_nop 0
	v_add_u32_e32 v130, v172, v149
	v_add_u32_e32 v131, v172, v137
	ds_read_b128 v[138:141], v130
	ds_read_b128 v[156:159], v131
	v_add_u32_e32 v130, v172, v136
	v_add_u32_e32 v131, v172, v135
	ds_read_b128 v[164:167], v130
	ds_read_b128 v[168:171], v131
	s_setprio 1
	v_mfma_f32_16x16x32_bf16 v[114:117], v[106:109], v[50:53], v[114:117]
	v_mfma_f32_16x16x32_bf16 v[106:109], v[106:109], v[82:85], v[110:113]
	v_mfma_f32_16x16x32_bf16 v[110:113], v[118:121], v[46:49], v[114:117]
	v_mfma_f32_16x16x32_bf16 v[106:109], v[118:121], v[78:81], v[106:109]
	v_mfma_f32_16x16x32_bf16 v[110:113], v[126:129], v[42:45], v[110:113]
	v_mfma_f32_16x16x32_bf16 v[106:109], v[126:129], v[74:77], v[106:109]
	v_mfma_f32_16x16x32_bf16 v[130:133], v[160:163], v[38:41], v[110:113]
	v_mfma_f32_16x16x32_bf16 v[106:109], v[160:163], v[70:73], v[106:109]
	s_setprio 0
	s_nop 3
	v_add_u32_e32 v110, v172, v150
	v_add_u32_e32 v114, v172, v151
	v_add_u32_e32 v118, v172, v152
	v_add_u32_e32 v126, v172, v153
	ds_read_b128 v[110:113], v110
	ds_read_b128 v[114:117], v114
	ds_read_b128 v[118:121], v118
	ds_read_b128 v[126:129], v126
	s_setprio 1
	s_waitcnt lgkmcnt(0)
	v_mfma_f32_16x16x32_bf16 v[160:163], v[138:141], v[66:69], 0
	v_mfma_f32_16x16x32_bf16 v[138:141], v[138:141], v[98:101], 0
	v_mfma_f32_16x16x32_bf16 v[160:163], v[156:159], v[62:65], v[160:163]
	v_mfma_f32_16x16x32_bf16 v[138:141], v[156:159], v[94:97], v[138:141]
	v_mfma_f32_16x16x32_bf16 v[156:159], v[164:167], v[58:61], v[160:163]
	v_mfma_f32_16x16x32_bf16 v[138:141], v[164:167], v[90:93], v[138:141]
	v_mfma_f32_16x16x32_bf16 v[156:159], v[168:171], v[54:57], v[156:159]
	v_mfma_f32_16x16x32_bf16 v[138:141], v[168:171], v[86:89], v[138:141]
	s_setprio 0
	v_add_u32_e32 v176, 0x16000, v134
	s_nop 0
	v_add_u32_e32 v160, v176, v149
	v_add_u32_e32 v164, v176, v137
	v_add_u32_e32 v168, v176, v136
	v_add_u32_e32 v172, v176, v135
	ds_read_b128 v[160:163], v160
	ds_read_b128 v[164:167], v164
	ds_read_b128 v[168:171], v168
	ds_read_b128 v[172:175], v172
	s_setprio 1
	v_mfma_f32_16x16x32_bf16 v[156:159], v[110:113], v[50:53], v[156:159]
	v_mfma_f32_16x16x32_bf16 v[110:113], v[110:113], v[82:85], v[138:141]
	v_mfma_f32_16x16x32_bf16 v[138:141], v[114:117], v[46:49], v[156:159]
	v_mfma_f32_16x16x32_bf16 v[110:113], v[114:117], v[78:81], v[110:113]
	v_mfma_f32_16x16x32_bf16 v[114:117], v[118:121], v[42:45], v[138:141]
	v_mfma_f32_16x16x32_bf16 v[110:113], v[118:121], v[74:77], v[110:113]
	v_mfma_f32_16x16x32_bf16 v[138:141], v[126:129], v[38:41], v[114:117]
	v_mfma_f32_16x16x32_bf16 v[110:113], v[126:129], v[70:73], v[110:113]
	s_setprio 0
	s_nop 3
	v_add_u32_e32 v114, v176, v150
	v_add_u32_e32 v118, v176, v151
	v_add_u32_e32 v126, v176, v152
	v_add_u32_e32 v156, v176, v153
	ds_read_b128 v[114:117], v114
	ds_read_b128 v[118:121], v118
	ds_read_b128 v[126:129], v126
	ds_read_b128 v[156:159], v156
	s_setprio 1
	s_waitcnt lgkmcnt(0)
	v_mfma_f32_16x16x32_bf16 v[176:179], v[160:163], v[66:69], 0
	v_mfma_f32_16x16x32_bf16 v[160:163], v[160:163], v[98:101], 0
	v_mfma_f32_16x16x32_bf16 v[176:179], v[164:167], v[62:65], v[176:179]
	v_mfma_f32_16x16x32_bf16 v[160:163], v[164:167], v[94:97], v[160:163]
	v_mfma_f32_16x16x32_bf16 v[164:167], v[168:171], v[58:61], v[176:179]
	v_mfma_f32_16x16x32_bf16 v[160:163], v[168:171], v[90:93], v[160:163]
	v_mfma_f32_16x16x32_bf16 v[164:167], v[172:175], v[54:57], v[164:167]
	v_mfma_f32_16x16x32_bf16 v[160:163], v[172:175], v[86:89], v[160:163]
	s_setprio 0
	v_add_u32_e32 v184, 0x18000, v134
	v_add_u32_e32 v168, v184, v149
	v_add_u32_e32 v172, v184, v137
	v_add_u32_e32 v176, v184, v136
	v_add_u32_e32 v180, v184, v135
	ds_read_b128 v[168:171], v168
	ds_read_b128 v[172:175], v172
	ds_read_b128 v[176:179], v176
	ds_read_b128 v[180:183], v180
	s_setprio 1
	v_mfma_f32_16x16x32_bf16 v[164:167], v[114:117], v[50:53], v[164:167]
	v_mfma_f32_16x16x32_bf16 v[114:117], v[114:117], v[82:85], v[160:163]
	v_mfma_f32_16x16x32_bf16 v[160:163], v[118:121], v[46:49], v[164:167]
	v_mfma_f32_16x16x32_bf16 v[114:117], v[118:121], v[78:81], v[114:117]
	v_mfma_f32_16x16x32_bf16 v[118:121], v[126:129], v[42:45], v[160:163]
	v_mfma_f32_16x16x32_bf16 v[114:117], v[126:129], v[74:77], v[114:117]
	v_mfma_f32_16x16x32_bf16 v[160:163], v[156:159], v[38:41], v[118:121]
	v_mfma_f32_16x16x32_bf16 v[114:117], v[156:159], v[70:73], v[114:117]
	s_setprio 0
	s_nop 3
	v_add_u32_e32 v118, v184, v150
	v_add_u32_e32 v126, v184, v151
	v_add_u32_e32 v156, v184, v152
	v_add_u32_e32 v164, v184, v153
	ds_read_b128 v[118:121], v118
	ds_read_b128 v[126:129], v126
	ds_read_b128 v[156:159], v156
	ds_read_b128 v[164:167], v164
	s_setprio 1
	s_waitcnt lgkmcnt(0)
	v_mfma_f32_16x16x32_bf16 v[184:187], v[168:171], v[66:69], 0
	v_mfma_f32_16x16x32_bf16 v[168:171], v[168:171], v[98:101], 0
	v_mfma_f32_16x16x32_bf16 v[184:187], v[172:175], v[62:65], v[184:187]
	v_mfma_f32_16x16x32_bf16 v[168:171], v[172:175], v[94:97], v[168:171]
	v_mfma_f32_16x16x32_bf16 v[172:175], v[176:179], v[58:61], v[184:187]
	v_mfma_f32_16x16x32_bf16 v[168:171], v[176:179], v[90:93], v[168:171]
	v_mfma_f32_16x16x32_bf16 v[172:175], v[180:183], v[54:57], v[172:175]
	v_mfma_f32_16x16x32_bf16 v[168:171], v[180:183], v[86:89], v[168:171]
	s_setprio 0
	v_add_u32_e32 v192, 0x1a000, v134
	v_add_u32_e32 v176, v192, v149
	v_add_u32_e32 v180, v192, v137
	v_add_u32_e32 v184, v192, v136
	v_add_u32_e32 v188, v192, v135
	ds_read_b128 v[176:179], v176
	ds_read_b128 v[180:183], v180
	ds_read_b128 v[184:187], v184
	ds_read_b128 v[188:191], v188
	s_setprio 1
	v_mfma_f32_16x16x32_bf16 v[172:175], v[118:121], v[50:53], v[172:175]
	v_mfma_f32_16x16x32_bf16 v[118:121], v[118:121], v[82:85], v[168:171]
	v_mfma_f32_16x16x32_bf16 v[168:171], v[126:129], v[46:49], v[172:175]
	v_mfma_f32_16x16x32_bf16 v[118:121], v[126:129], v[78:81], v[118:121]
	v_mfma_f32_16x16x32_bf16 v[126:129], v[156:159], v[42:45], v[168:171]
	v_mfma_f32_16x16x32_bf16 v[118:121], v[156:159], v[74:77], v[118:121]
	v_mfma_f32_16x16x32_bf16 v[156:159], v[164:167], v[38:41], v[126:129]
	v_mfma_f32_16x16x32_bf16 v[118:121], v[164:167], v[70:73], v[118:121]
	s_setprio 0
	s_nop 3
	v_add_u32_e32 v126, v192, v150
	v_add_u32_e32 v164, v192, v151
	v_add_u32_e32 v168, v192, v152
	v_add_u32_e32 v172, v192, v153
	ds_read_b128 v[126:129], v126
	ds_read_b128 v[164:167], v164
	ds_read_b128 v[168:171], v168
	ds_read_b128 v[172:175], v172
	s_setprio 1
	s_waitcnt lgkmcnt(0)
	v_mfma_f32_16x16x32_bf16 v[192:195], v[176:179], v[66:69], 0
	v_mfma_f32_16x16x32_bf16 v[176:179], v[176:179], v[98:101], 0
	v_mfma_f32_16x16x32_bf16 v[192:195], v[180:183], v[62:65], v[192:195]
	v_mfma_f32_16x16x32_bf16 v[176:179], v[180:183], v[94:97], v[176:179]
	v_mfma_f32_16x16x32_bf16 v[180:183], v[184:187], v[58:61], v[192:195]
	v_mfma_f32_16x16x32_bf16 v[176:179], v[184:187], v[90:93], v[176:179]
	v_mfma_f32_16x16x32_bf16 v[180:183], v[188:191], v[54:57], v[180:183]
	v_mfma_f32_16x16x32_bf16 v[176:179], v[188:191], v[86:89], v[176:179]
	s_setprio 0
	v_add_u32_e32 v200, 0x1c000, v134
	v_add_u32_e32 v184, v200, v149
	v_add_u32_e32 v188, v200, v137
	v_add_u32_e32 v192, v200, v136
	v_add_u32_e32 v196, v200, v135
	ds_read_b128 v[184:187], v184
	ds_read_b128 v[188:191], v188
	ds_read_b128 v[192:195], v192
	ds_read_b128 v[196:199], v196
	s_setprio 1
	v_mfma_f32_16x16x32_bf16 v[180:183], v[126:129], v[50:53], v[180:183]
	v_mfma_f32_16x16x32_bf16 v[126:129], v[126:129], v[82:85], v[176:179]
	v_mfma_f32_16x16x32_bf16 v[176:179], v[164:167], v[46:49], v[180:183]
	v_mfma_f32_16x16x32_bf16 v[126:129], v[164:167], v[78:81], v[126:129]
	v_mfma_f32_16x16x32_bf16 v[164:167], v[168:171], v[42:45], v[176:179]
	v_mfma_f32_16x16x32_bf16 v[126:129], v[168:171], v[74:77], v[126:129]
	v_mfma_f32_16x16x32_bf16 v[164:167], v[172:175], v[38:41], v[164:167]
	v_mfma_f32_16x16x32_bf16 v[126:129], v[172:175], v[70:73], v[126:129]
	s_setprio 0
	v_add_u32_e32 v168, v200, v150
	v_add_u32_e32 v172, v200, v151
	v_add_u32_e32 v176, v200, v152
	v_add_u32_e32 v180, v200, v153
	ds_read_b128 v[168:171], v168
	ds_read_b128 v[172:175], v172
	ds_read_b128 v[176:179], v176
	ds_read_b128 v[180:183], v180
	s_setprio 1
	s_waitcnt lgkmcnt(0)
	v_mfma_f32_16x16x32_bf16 v[200:203], v[184:187], v[66:69], 0
	v_mfma_f32_16x16x32_bf16 v[184:187], v[184:187], v[98:101], 0
	v_mfma_f32_16x16x32_bf16 v[200:203], v[188:191], v[62:65], v[200:203]
	v_mfma_f32_16x16x32_bf16 v[184:187], v[188:191], v[94:97], v[184:187]
	v_mfma_f32_16x16x32_bf16 v[188:191], v[192:195], v[58:61], v[200:203]
	v_mfma_f32_16x16x32_bf16 v[184:187], v[192:195], v[90:93], v[184:187]
	v_mfma_f32_16x16x32_bf16 v[188:191], v[196:199], v[54:57], v[188:191]
	v_mfma_f32_16x16x32_bf16 v[184:187], v[196:199], v[86:89], v[184:187]
	s_setprio 0
	v_add_u32_e32 v208, 0x1e000, v134
	v_add_u32_e32 v134, v208, v149
	v_add_u32_e32 v137, v208, v137
	ds_read_b128 v[192:195], v134
	ds_read_b128 v[196:199], v137
	v_add_u32_e32 v134, v208, v136
	v_add_u32_e32 v135, v208, v135
	ds_read_b128 v[200:203], v134
	ds_read_b128 v[204:207], v135
	s_setprio 1
	v_mfma_f32_16x16x32_bf16 v[134:137], v[168:171], v[50:53], v[188:191]
	v_mfma_f32_16x16x32_bf16 v[168:171], v[168:171], v[82:85], v[184:187]
	v_mfma_f32_16x16x32_bf16 v[134:137], v[172:175], v[46:49], v[134:137]
	v_mfma_f32_16x16x32_bf16 v[168:171], v[172:175], v[78:81], v[168:171]
	v_mfma_f32_16x16x32_bf16 v[134:137], v[176:179], v[42:45], v[134:137]
	v_mfma_f32_16x16x32_bf16 v[168:171], v[176:179], v[74:77], v[168:171]
	v_mfma_f32_16x16x32_bf16 v[172:175], v[180:183], v[38:41], v[134:137]
	v_mfma_f32_16x16x32_bf16 v[134:137], v[180:183], v[70:73], v[168:171]
	s_setprio 0
	v_add_u32_e32 v149, v208, v150
	v_add_u32_e32 v150, v208, v151
	s_nop 2
	ds_read_b128 v[168:171], v149
	ds_read_b128 v[176:179], v150
	v_add_u32_e32 v149, v208, v152
	v_add_u32_e32 v180, v208, v153
	ds_read_b128 v[150:153], v149
	ds_read_b128 v[180:183], v180
	s_setprio 1
	s_waitcnt lgkmcnt(0)
	v_mfma_f32_16x16x32_bf16 v[66:69], v[192:195], v[66:69], 0
	v_mfma_f32_16x16x32_bf16 v[98:101], v[192:195], v[98:101], 0
	v_mfma_f32_16x16x32_bf16 v[62:65], v[196:199], v[62:65], v[66:69]
	v_mfma_f32_16x16x32_bf16 v[66:69], v[196:199], v[94:97], v[98:101]
	v_mfma_f32_16x16x32_bf16 v[58:61], v[200:203], v[58:61], v[62:65]
	v_mfma_f32_16x16x32_bf16 v[62:65], v[200:203], v[90:93], v[66:69]
	v_mfma_f32_16x16x32_bf16 v[54:57], v[204:207], v[54:57], v[58:61]
	v_mfma_f32_16x16x32_bf16 v[58:61], v[204:207], v[86:89], v[62:65]
	s_setprio 0
	s_setprio 1
	v_mfma_f32_16x16x32_bf16 v[50:53], v[168:171], v[50:53], v[54:57]
	v_mfma_f32_16x16x32_bf16 v[54:57], v[168:171], v[82:85], v[58:61]
	v_mfma_f32_16x16x32_bf16 v[46:49], v[176:179], v[46:49], v[50:53]
	v_mfma_f32_16x16x32_bf16 v[50:53], v[176:179], v[78:81], v[54:57]
	v_mfma_f32_16x16x32_bf16 v[42:45], v[150:153], v[42:45], v[46:49]
	v_mfma_f32_16x16x32_bf16 v[46:49], v[150:153], v[74:77], v[50:53]
	v_mfma_f32_16x16x32_bf16 v[50:53], v[180:183], v[38:41], v[42:45]
	v_mfma_f32_16x16x32_bf16 v[66:69], v[180:183], v[70:73], v[46:49]
	s_setprio 0
	v_mul_f32_e32 v39, v148, v130
	v_mul_f32_e32 v38, v148, v122
	v_exp_f32_e32 v40, v39
	v_mul_f32_e32 v39, v148, v123
	v_mul_f32_e32 v42, v148, v124
	v_mul_f32_e32 v44, v148, v125
	v_exp_f32_e32 v38, v38
	v_exp_f32_e32 v39, v39
	v_mul_f32_e32 v41, v148, v131
	v_exp_f32_e32 v42, v42
	v_mul_f32_e32 v43, v148, v132
	v_exp_f32_e32 v44, v44
	v_mul_f32_e32 v45, v148, v133
	v_exp_f32_e32 v41, v41
	v_exp_f32_e32 v43, v43
	v_exp_f32_e32 v45, v45
	v_add_f32_e32 v46, v38, v39
	v_add_f32_e32 v47, v42, v44
	v_add_f32_e32 v46, v46, v47
	v_add_f32_e32 v47, v40, v41
	v_add_f32_e32 v48, v43, v45
	v_add_f32_e32 v47, v47, v48
	v_cvt_pk_bf16_f32 v40, v40, v41
	v_cvt_pk_bf16_f32 v41, v43, v45
	v_mul_f32_e32 v43, v148, v160
	v_add_f32_e32 v46, v46, v47
	v_cvt_pk_bf16_f32 v38, v38, v39
	v_cvt_pk_bf16_f32 v39, v42, v44
	v_mul_f32_e32 v42, v148, v138
	v_exp_f32_e32 v44, v43
	v_mul_f32_e32 v43, v148, v139
	v_mul_f32_e32 v47, v148, v140
	v_mul_f32_e32 v49, v148, v141
	v_exp_f32_e32 v42, v42
	v_exp_f32_e32 v43, v43
	v_mul_f32_e32 v45, v148, v161
	v_exp_f32_e32 v47, v47
	v_mul_f32_e32 v48, v148, v162
	v_exp_f32_e32 v49, v49
	v_mul_f32_e32 v54, v148, v163
	v_exp_f32_e32 v45, v45
	v_exp_f32_e32 v48, v48
	v_exp_f32_e32 v54, v54
	v_add_f32_e32 v55, v42, v43
	v_add_f32_e32 v56, v47, v49
	v_add_f32_e32 v55, v55, v56
	v_add_f32_e32 v56, v44, v45
	v_add_f32_e32 v57, v48, v54
	v_add_f32_e32 v56, v56, v57
	v_add_f32_e32 v46, v155, v46
	v_add_f32_e32 v55, v55, v56
	v_add_f32_e32 v46, v46, v55
	v_cvt_pk_bf16_f32 v42, v42, v43
	v_cvt_pk_bf16_f32 v43, v47, v49
	v_mul_f32_e32 v47, v148, v156
	v_mul_f32_e32 v49, v148, v157
	v_mul_f32_e32 v55, v148, v158
	v_mul_f32_e32 v57, v148, v159
	v_cvt_pk_bf16_f32 v44, v44, v45
	v_cvt_pk_bf16_f32 v45, v48, v54
	v_exp_f32_e32 v47, v47
	v_mul_f32_e32 v48, v148, v164
	v_exp_f32_e32 v49, v49
	v_mul_f32_e32 v54, v148, v165
	v_exp_f32_e32 v55, v55
	v_mul_f32_e32 v56, v148, v166
	v_exp_f32_e32 v57, v57
	v_mul_f32_e32 v58, v148, v167
	v_exp_f32_e32 v48, v48
	v_exp_f32_e32 v54, v54
	v_exp_f32_e32 v56, v56
	v_exp_f32_e32 v58, v58
	v_add_f32_e32 v59, v47, v49
	v_add_f32_e32 v60, v55, v57
	v_add_f32_e32 v59, v59, v60
	v_add_f32_e32 v60, v48, v54
	v_add_f32_e32 v61, v56, v58
	v_add_f32_e32 v60, v60, v61
	v_add_f32_e32 v59, v59, v60
	v_mul_f32_e32 v50, v148, v50
	v_mul_f32_e32 v51, v148, v51
	v_mul_f32_e32 v52, v148, v52
	v_add_f32_e32 v59, v46, v59
	v_cvt_pk_bf16_f32 v46, v47, v49
	v_cvt_pk_bf16_f32 v47, v55, v57
	v_cvt_pk_bf16_f32 v48, v48, v54
	v_cvt_pk_bf16_f32 v49, v56, v58
	v_mul_f32_e32 v54, v148, v172
	v_exp_f32_e32 v55, v50
	v_mul_f32_e32 v50, v148, v173
	v_exp_f32_e32 v56, v51
	v_mul_f32_e32 v51, v148, v174
	v_exp_f32_e32 v57, v52
	v_mul_f32_e32 v52, v148, v175
	v_exp_f32_e32 v54, v54
	v_exp_f32_e32 v50, v50
	v_exp_f32_e32 v51, v51
	v_exp_f32_e32 v52, v52
	v_mul_f32_e32 v53, v148, v53
	v_exp_f32_e32 v53, v53
	v_add_f32_e32 v58, v54, v50
	v_add_f32_e32 v60, v51, v52
	v_add_f32_e32 v58, v58, v60
	v_add_f32_e32 v60, v55, v56
	v_add_f32_e32 v61, v57, v53
	v_add_f32_e32 v60, v60, v61
	v_add_f32_e32 v58, v58, v60
	v_cvt_pk_bf16_f32 v51, v51, v52
	v_cvt_pk_bf16_f32 v52, v55, v56
	v_mul_f32_e32 v55, v147, v106
	v_add_f32_e32 v74, v59, v58
	v_cvt_pk_bf16_f32 v50, v54, v50
	v_mul_f32_e32 v54, v147, v102
	v_exp_f32_e32 v56, v55
	v_mul_f32_e32 v55, v147, v103
	v_mul_f32_e32 v58, v147, v104
	v_mul_f32_e32 v60, v147, v105
	v_cvt_pk_bf16_f32 v53, v57, v53
	v_exp_f32_e32 v54, v54
	v_exp_f32_e32 v55, v55
	v_mul_f32_e32 v57, v147, v107
	v_exp_f32_e32 v58, v58
	v_mul_f32_e32 v59, v147, v108
	v_exp_f32_e32 v60, v60
	v_mul_f32_e32 v61, v147, v109
	v_exp_f32_e32 v57, v57
	v_exp_f32_e32 v59, v59
	v_exp_f32_e32 v61, v61
	v_add_f32_e32 v62, v54, v55
	v_add_f32_e32 v63, v58, v60
	v_add_f32_e32 v62, v62, v63
	v_add_f32_e32 v63, v56, v57
	v_add_f32_e32 v64, v59, v61
	v_add_f32_e32 v63, v63, v64
	v_cvt_pk_bf16_f32 v56, v56, v57
	v_cvt_pk_bf16_f32 v57, v59, v61
	v_mul_f32_e32 v59, v147, v114
	v_add_f32_e32 v62, v62, v63
	v_cvt_pk_bf16_f32 v54, v54, v55
	v_cvt_pk_bf16_f32 v55, v58, v60
	v_mul_f32_e32 v58, v147, v110
	v_exp_f32_e32 v60, v59
	v_mul_f32_e32 v59, v147, v111
	v_mul_f32_e32 v63, v147, v112
	v_mul_f32_e32 v65, v147, v113
	v_exp_f32_e32 v58, v58
	v_exp_f32_e32 v59, v59
	v_mul_f32_e32 v61, v147, v115
	v_exp_f32_e32 v63, v63
	v_mul_f32_e32 v64, v147, v116
	v_exp_f32_e32 v65, v65
	v_mul_f32_e32 v70, v147, v117
	v_exp_f32_e32 v61, v61
	v_exp_f32_e32 v64, v64
	v_exp_f32_e32 v70, v70
	v_add_f32_e32 v71, v58, v59
	v_add_f32_e32 v72, v63, v65
	v_add_f32_e32 v71, v71, v72
	v_add_f32_e32 v72, v60, v61
	v_add_f32_e32 v73, v64, v70
	v_add_f32_e32 v72, v72, v73
	v_add_f32_e32 v62, v154, v62
	v_add_f32_e32 v71, v71, v72
	v_add_f32_e32 v62, v62, v71
	v_cvt_pk_bf16_f32 v58, v58, v59
	v_cvt_pk_bf16_f32 v59, v63, v65
	v_mul_f32_e32 v63, v147, v118
	v_mul_f32_e32 v65, v147, v119
	v_mul_f32_e32 v71, v147, v120
	v_mul_f32_e32 v73, v147, v121
	v_cvt_pk_bf16_f32 v60, v60, v61
	v_cvt_pk_bf16_f32 v61, v64, v70
	v_exp_f32_e32 v63, v63
	v_mul_f32_e32 v64, v147, v126
	v_exp_f32_e32 v65, v65
	v_mul_f32_e32 v70, v147, v127
	v_exp_f32_e32 v71, v71
	v_mul_f32_e32 v72, v147, v128
	v_exp_f32_e32 v73, v73
	v_mul_f32_e32 v75, v147, v129
	v_exp_f32_e32 v64, v64
	v_exp_f32_e32 v70, v70
	v_exp_f32_e32 v72, v72
	v_exp_f32_e32 v75, v75
	v_add_f32_e32 v76, v63, v65
	v_add_f32_e32 v77, v71, v73
	v_add_f32_e32 v76, v76, v77
	v_add_f32_e32 v77, v64, v70
	v_add_f32_e32 v78, v72, v75
	v_add_f32_e32 v77, v77, v78
	v_add_f32_e32 v76, v76, v77
	v_mul_f32_e32 v66, v147, v66
	v_mul_f32_e32 v67, v147, v67
	v_mul_f32_e32 v68, v147, v68
	v_add_f32_e32 v76, v62, v76
	v_cvt_pk_bf16_f32 v62, v63, v65
	v_cvt_pk_bf16_f32 v63, v71, v73
	v_cvt_pk_bf16_f32 v64, v64, v70
	v_cvt_pk_bf16_f32 v65, v72, v75
	v_mul_f32_e32 v70, v147, v134
	v_exp_f32_e32 v71, v66
	v_mul_f32_e32 v66, v147, v135
	v_exp_f32_e32 v72, v67
	v_mul_f32_e32 v67, v147, v136
	v_exp_f32_e32 v73, v68
	v_mul_f32_e32 v68, v147, v137
	v_exp_f32_e32 v70, v70
	v_exp_f32_e32 v66, v66
	v_exp_f32_e32 v67, v67
	v_exp_f32_e32 v68, v68
	v_mul_f32_e32 v69, v147, v69
	v_exp_f32_e32 v69, v69
	v_add_f32_e32 v75, v70, v66
	v_add_f32_e32 v77, v67, v68
	v_add_f32_e32 v75, v75, v77
	v_add_f32_e32 v77, v71, v72
	v_add_f32_e32 v78, v73, v69
	v_add_f32_e32 v77, v77, v78
	v_add_f32_e32 v75, v75, v77
	v_add_f32_e32 v75, v76, v75
	s_waitcnt vmcnt(0)
	s_barrier
	s_add_i32 s9, s8, 64
	v_ashrrev_i32_e32 v76, 5, v5
	v_cvt_pk_bf16_f32 v66, v70, v66
	v_lshl_add_u32 v70, s9, 1, v76
	v_cvt_pk_bf16_f32 v67, v67, v68
	v_cvt_pk_bf16_f32 v68, v71, v72
	v_lshrrev_b32_e32 v71, 1, v70
	v_and_b32_e32 v5, 31, v5
	v_and_b32_e32 v71, 12, v71
	v_and_b32_e32 v77, 3, v76
	v_bitop3_b32 v72, v71, v5, v77 bitop3:0x36
	v_ashrrev_i32_e32 v71, 31, v70
	v_lshlrev_b64 v[70:71], 9, v[70:71]
	v_cvt_pk_bf16_f32 v69, v73, v69
	v_lshl_add_u64 v[70:71], s[4:5], 0, v[70:71]
	v_lshlrev_b32_e32 v72, 4, v72
	v_mov_b32_e32 v73, v4
	s_lshl_b32 s9, s9, 10
	v_lshl_add_u64 v[70:71], v[70:71], 0, v[72:73]
	s_add_i32 m0, s9, 0
	s_add_i32 s9, s8, 0x41
	global_load_lds_dwordx4 v[70:71], off
	v_lshl_add_u32 v70, s9, 1, v76
	v_lshrrev_b32_e32 v71, 1, v70
	v_and_b32_e32 v71, 12, v71
	v_and_b32_e32 v72, 3, v70
	v_bitop3_b32 v72, v71, v5, v72 bitop3:0x36
	v_ashrrev_i32_e32 v71, 31, v70
	v_lshlrev_b64 v[70:71], 9, v[70:71]
	v_lshl_add_u64 v[70:71], s[4:5], 0, v[70:71]
	v_lshlrev_b32_e32 v72, 4, v72
	s_lshl_b32 s9, s9, 10
	v_lshl_add_u64 v[70:71], v[70:71], 0, v[72:73]
	s_add_i32 m0, s9, 0
	s_add_i32 s9, s8, 0x42
	global_load_lds_dwordx4 v[70:71], off
	v_lshl_add_u32 v70, s9, 1, v76
	v_lshrrev_b32_e32 v71, 1, v70
	v_and_b32_e32 v71, 12, v71
	v_bitop3_b32 v72, v71, v5, v77 bitop3:0x36
	v_ashrrev_i32_e32 v71, 31, v70
	v_lshlrev_b64 v[70:71], 9, v[70:71]
	v_lshl_add_u64 v[70:71], s[4:5], 0, v[70:71]
	v_lshlrev_b32_e32 v72, 4, v72
	s_lshl_b32 s9, s9, 10
	v_lshl_add_u64 v[70:71], v[70:71], 0, v[72:73]
	s_add_i32 m0, s9, 0
	s_add_i32 s9, s8, 0x43
	global_load_lds_dwordx4 v[70:71], off
	v_lshl_add_u32 v70, s9, 1, v76
	v_lshrrev_b32_e32 v71, 1, v70
	v_and_b32_e32 v71, 12, v71
	v_and_b32_e32 v72, 3, v70
	v_bitop3_b32 v72, v71, v5, v72 bitop3:0x36
	v_ashrrev_i32_e32 v71, 31, v70
	v_lshlrev_b64 v[70:71], 9, v[70:71]
	v_lshl_add_u64 v[70:71], s[4:5], 0, v[70:71]
	v_lshlrev_b32_e32 v72, 4, v72
	s_lshl_b32 s9, s9, 10
	v_lshl_add_u64 v[70:71], v[70:71], 0, v[72:73]
	s_add_i32 m0, s9, 0
	s_add_i32 s9, s8, 0x44
	global_load_lds_dwordx4 v[70:71], off
	v_lshl_add_u32 v70, s9, 1, v76
	v_lshrrev_b32_e32 v71, 1, v70
	v_and_b32_e32 v71, 12, v71
	v_bitop3_b32 v72, v71, v5, v77 bitop3:0x36
	v_ashrrev_i32_e32 v71, 31, v70
	v_lshlrev_b64 v[70:71], 9, v[70:71]
	v_lshl_add_u64 v[70:71], s[4:5], 0, v[70:71]
	v_lshlrev_b32_e32 v72, 4, v72
	s_lshl_b32 s9, s9, 10
	v_lshl_add_u64 v[70:71], v[70:71], 0, v[72:73]
	s_add_i32 m0, s9, 0
	s_add_i32 s9, s8, 0x45
	global_load_lds_dwordx4 v[70:71], off
	v_lshl_add_u32 v70, s9, 1, v76
	v_lshrrev_b32_e32 v71, 1, v70
	v_and_b32_e32 v71, 12, v71
	v_and_b32_e32 v72, 3, v70
	v_bitop3_b32 v72, v71, v5, v72 bitop3:0x36
	v_ashrrev_i32_e32 v71, 31, v70
	v_lshlrev_b64 v[70:71], 9, v[70:71]
	v_lshl_add_u64 v[70:71], s[4:5], 0, v[70:71]
	v_lshlrev_b32_e32 v72, 4, v72
	s_lshl_b32 s9, s9, 10
	v_lshl_add_u64 v[70:71], v[70:71], 0, v[72:73]
	s_add_i32 m0, s9, 0
	s_add_i32 s9, s8, 0x46
	global_load_lds_dwordx4 v[70:71], off
	v_lshl_add_u32 v70, s9, 1, v76
	v_lshrrev_b32_e32 v71, 1, v70
	v_and_b32_e32 v71, 12, v71
	v_bitop3_b32 v72, v71, v5, v77 bitop3:0x36
	v_ashrrev_i32_e32 v71, 31, v70
	v_lshlrev_b64 v[70:71], 9, v[70:71]
	v_lshl_add_u64 v[70:71], s[4:5], 0, v[70:71]
	v_lshlrev_b32_e32 v72, 4, v72
	s_lshl_b32 s9, s9, 10
	v_lshl_add_u64 v[70:71], v[70:71], 0, v[72:73]
	s_add_i32 m0, s9, 0
	s_addk_i32 s8, 0x47
	global_load_lds_dwordx4 v[70:71], off
	v_lshl_add_u32 v70, s8, 1, v76
	v_lshrrev_b32_e32 v71, 1, v70
	v_and_b32_e32 v71, 12, v71
	v_and_b32_e32 v72, 3, v70
	v_bitop3_b32 v5, v71, v5, v72 bitop3:0x36
	v_ashrrev_i32_e32 v71, 31, v70
	v_lshlrev_b64 v[70:71], 9, v[70:71]
	v_lshl_add_u64 v[70:71], s[4:5], 0, v[70:71]
	v_lshlrev_b32_e32 v72, 4, v5
	s_lshl_b32 s4, s8, 10
	v_lshl_add_u64 v[70:71], v[70:71], 0, v[72:73]
	s_add_i32 m0, s4, 0
	v_mov_b32_e32 v5, v74
	global_load_lds_dwordx4 v[70:71], off
	s_nop 0
	v_permlane16_swap_b32_e32 v74, v5
	v_add_f32_e32 v5, v74, v5
	v_mov_b32_e32 v70, v5
	s_nop 1
	v_permlane32_swap_b32_e32 v5, v70
	v_add_f32_e32 v5, v5, v70
	v_div_scale_f32 v70, s[4:5], v5, v5, 1.0
	v_rcp_f32_e32 v71, v70
	v_lshl_add_u64 v[2:3], s[2:3], 0, v[2:3]
	v_bfe_u32 v87, v145, 5, 1
	v_lshl_add_u64 v[2:3], v[2:3], 0, s[6:7]
	v_fma_f32 v72, -v70, v71, 1.0
	v_fmac_f32_e32 v71, v72, v71
	v_div_scale_f32 v72, vcc, 1.0, v5, 1.0
	v_mul_f32_e32 v73, v72, v71
	v_fma_f32 v74, -v70, v73, v72
	v_fmac_f32_e32 v73, v74, v71
	v_fma_f32 v70, -v70, v73, v72
	v_div_fmas_f32 v70, v70, v71, v73
	v_div_fixup_f32 v5, v70, v5, 1.0
	v_mov_b32_e32 v70, v75
	s_nop 1
	v_permlane16_swap_b32_e32 v75, v70
	v_add_f32_e32 v70, v75, v70
	v_mov_b32_e32 v71, v70
	s_nop 1
	v_permlane32_swap_b32_e32 v70, v71
	v_add_f32_e32 v70, v70, v71
	v_div_scale_f32 v71, s[4:5], v70, v70, 1.0
	v_rcp_f32_e32 v72, v71
	v_bitop3_b32 v76, v87, v144, 8 bitop3:0x36
	v_bitop3_b32 v77, v87, v144, 10 bitop3:0x36
	v_bitop3_b32 v78, v87, v144, 12 bitop3:0x36
	v_fma_f32 v73, -v71, v72, 1.0
	v_fmac_f32_e32 v72, v73, v72
	v_div_scale_f32 v73, vcc, 1.0, v70, 1.0
	v_mul_f32_e32 v74, v73, v72
	v_fma_f32 v75, -v71, v74, v73
	v_fmac_f32_e32 v74, v75, v72
	v_fma_f32 v71, -v71, v74, v73
	v_div_fmas_f32 v71, v71, v72, v74
	v_lshlrev_b32_e32 v72, 1, v145
	v_and_b32_e32 v73, 3, v145
	v_and_or_b32 v72, v72, 24, v73
	v_and_b32_e32 v73, 8, v146
	v_lshlrev_b32_e32 v72, 9, v72
	v_add3_u32 v146, 0, v73, v72
	v_bitop3_b32 v72, v87, v145, 15 bitop3:0x78
	v_bitop3_b32 v73, v87, v144, 2 bitop3:0x36
	v_bitop3_b32 v74, v87, v144, 4 bitop3:0x36
	v_bitop3_b32 v75, v87, v144, 6 bitop3:0x36
	v_bitop3_b32 v79, v87, v144, 14 bitop3:0x36
	v_bitop3_b32 v80, v87, v144, 16 bitop3:0x36
	v_bitop3_b32 v81, v87, v144, 18 bitop3:0x36
	v_bitop3_b32 v82, v87, v144, 20 bitop3:0x36
	v_bitop3_b32 v83, v87, v144, 22 bitop3:0x36
	v_bitop3_b32 v84, v87, v144, 24 bitop3:0x36
	v_bitop3_b32 v85, v87, v144, 26 bitop3:0x36
	v_bitop3_b32 v86, v87, v144, 28 bitop3:0x36
	v_bitop3_b32 v87, v87, v144, 30 bitop3:0x36
	v_div_fixup_f32 v136, v71, v70, 1.0
	v_lshl_add_u64 v[70:71], v[2:3], 0, v[142:143]
	v_lshlrev_b32_e32 v149, 4, v72
	v_lshlrev_b32_e32 v151, 4, v73
	v_lshlrev_b32_e32 v153, 4, v74
	v_lshlrev_b32_e32 v154, 4, v75
	v_lshlrev_b32_e32 v143, 4, v76
	v_lshlrev_b32_e32 v147, 4, v77
	v_lshlrev_b32_e32 v150, 4, v78
	v_lshlrev_b32_e32 v152, 4, v79
	v_lshlrev_b32_e32 v139, 4, v80
	v_lshlrev_b32_e32 v141, 4, v81
	v_lshlrev_b32_e32 v145, 4, v82
	v_lshlrev_b32_e32 v148, 4, v83
	v_lshlrev_b32_e32 v137, 4, v84
	v_lshlrev_b32_e32 v138, 4, v85
	v_lshlrev_b32_e32 v140, 4, v86
	v_lshlrev_b32_e32 v142, 4, v87
	v_add_u32_e32 v72, v146, v149
	v_add_u32_e32 v73, v146, v151
	v_add_u32_e32 v74, v146, v153
	v_add_u32_e32 v75, v146, v154
	v_add_u32_e32 v76, v146, v143
	v_add_u32_e32 v77, v146, v147
	v_add_u32_e32 v78, v146, v150
	v_add_u32_e32 v79, v146, v152
	v_add_u32_e32 v80, v146, v139
	v_add_u32_e32 v81, v146, v141
	v_add_u32_e32 v82, v146, v145
	v_add_u32_e32 v83, v146, v148
	v_add_u32_e32 v84, v146, v137
	v_add_u32_e32 v85, v146, v138
	v_add_u32_e32 v86, v146, v140
	v_add_u32_e32 v87, v146, v142
	s_waitcnt vmcnt(8)
	s_waitcnt lgkmcnt(0)
	s_barrier
	ds_read2st64_b64 v[88:91], v72 offset1:4
	ds_read2st64_b64 v[92:95], v73 offset1:4
	ds_read2st64_b64 v[96:99], v74 offset1:4
	ds_read2st64_b64 v[100:103], v75 offset1:4
	ds_read2st64_b64 v[104:107], v76 offset1:4
	ds_read2st64_b64 v[108:111], v77 offset1:4
	ds_read2st64_b64 v[112:115], v78 offset1:4
	ds_read2st64_b64 v[116:119], v79 offset1:4
	ds_read2st64_b64 v[120:123], v80 offset1:4
	ds_read2st64_b64 v[124:127], v81 offset1:4
	ds_read2st64_b64 v[128:131], v82 offset1:4
	ds_read2st64_b64 v[132:135], v83 offset1:4
	ds_read2st64_b64 v[156:159], v84 offset1:4
	ds_read2st64_b64 v[160:163], v85 offset1:4
	ds_read2st64_b64 v[164:167], v86 offset1:4
	ds_read2st64_b64 v[168:171], v87 offset1:4
	s_mov_b64 s[2:3], 0xae00000
	v_lshl_add_u64 v[2:3], v[70:71], 0, s[2:3]
	s_setprio 1
	s_waitcnt lgkmcnt(14)
	v_mov_b32_e32 v172, v88
	v_mov_b32_e32 v173, v89
	v_mov_b32_e32 v174, v92
	v_mov_b32_e32 v175, v93
	s_waitcnt lgkmcnt(13)
	v_mov_b32_e32 v180, v96
	v_mov_b32_e32 v181, v97
	s_waitcnt lgkmcnt(12)
	v_mov_b32_e32 v182, v100
	v_mov_b32_e32 v183, v101
	v_mfma_f32_16x16x32_bf16 v[176:179], v[172:175], v[6:9], 0
	v_mfma_f32_16x16x32_bf16 v[172:175], v[172:175], v[22:25], 0
	v_mfma_f32_16x16x32_bf16 v[176:179], v[180:183], v[10:13], v[176:179]
	v_mfma_f32_16x16x32_bf16 v[172:175], v[180:183], v[26:29], v[172:175]
	s_waitcnt lgkmcnt(11)
	v_mov_b32_e32 v180, v104
	v_mov_b32_e32 v181, v105
	s_waitcnt lgkmcnt(10)
	v_mov_b32_e32 v182, v108
	v_mov_b32_e32 v183, v109
	s_nop 1
	v_mfma_f32_16x16x32_bf16 v[176:179], v[180:183], v[14:17], v[176:179]
	v_mfma_f32_16x16x32_bf16 v[172:175], v[180:183], v[30:33], v[172:175]
	s_waitcnt lgkmcnt(9)
	v_mov_b32_e32 v180, v112
	v_mov_b32_e32 v181, v113
	s_waitcnt lgkmcnt(8)
	v_mov_b32_e32 v182, v116
	v_mov_b32_e32 v183, v117
	s_nop 1
	v_mfma_f32_16x16x32_bf16 v[176:179], v[180:183], v[18:21], v[176:179]
	v_mfma_f32_16x16x32_bf16 v[172:175], v[180:183], v[34:37], v[172:175]
	s_waitcnt lgkmcnt(7)
	v_mov_b32_e32 v180, v120
	v_mov_b32_e32 v181, v121
	s_waitcnt lgkmcnt(6)
	v_mov_b32_e32 v182, v124
	v_mov_b32_e32 v183, v125
	s_nop 1
	v_mfma_f32_16x16x32_bf16 v[176:179], v[180:183], v[38:41], v[176:179]
	v_mfma_f32_16x16x32_bf16 v[172:175], v[180:183], v[54:57], v[172:175]
	s_waitcnt lgkmcnt(5)
	v_mov_b32_e32 v180, v128
	v_mov_b32_e32 v181, v129
	s_waitcnt lgkmcnt(4)
	v_mov_b32_e32 v182, v132
	v_mov_b32_e32 v183, v133
	s_nop 1
	v_mfma_f32_16x16x32_bf16 v[176:179], v[180:183], v[42:45], v[176:179]
	v_mfma_f32_16x16x32_bf16 v[172:175], v[180:183], v[58:61], v[172:175]
	s_waitcnt lgkmcnt(3)
	v_mov_b32_e32 v180, v156
	v_mov_b32_e32 v181, v157
	s_waitcnt lgkmcnt(2)
	v_mov_b32_e32 v182, v160
	v_mov_b32_e32 v183, v161
	s_nop 1
	v_mfma_f32_16x16x32_bf16 v[176:179], v[180:183], v[46:49], v[176:179]
	v_mfma_f32_16x16x32_bf16 v[172:175], v[180:183], v[62:65], v[172:175]
	s_waitcnt lgkmcnt(1)
	v_mov_b32_e32 v180, v164
	v_mov_b32_e32 v181, v165
	s_waitcnt lgkmcnt(0)
	v_mov_b32_e32 v182, v168
	v_mov_b32_e32 v183, v169
	s_nop 1
	v_mfma_f32_16x16x32_bf16 v[176:179], v[180:183], v[50:53], v[176:179]
	v_mfma_f32_16x16x32_bf16 v[172:175], v[180:183], v[66:69], v[172:175]
	s_setprio 0
	s_nop 5
	v_mul_f32_e32 v88, v5, v176
	v_mul_f32_e32 v89, v5, v177
	v_cvt_pk_bf16_f32 v88, v88, v89
	v_mul_f32_e32 v89, v5, v178
	v_mul_f32_e32 v92, v5, v179
	v_cvt_pk_bf16_f32 v89, v89, v92
	v_mul_f32_e32 v92, v136, v172
	v_mul_f32_e32 v93, v136, v173
	v_cvt_pk_bf16_f32 v96, v92, v93
	v_mul_f32_e32 v92, v136, v174
	v_mul_f32_e32 v93, v136, v175
	ds_read_b64 v[172:173], v72 offset:16384
	ds_read_b64 v[174:175], v73 offset:16384
	ds_read_b64 v[176:177], v74 offset:16384
	ds_read_b64 v[178:179], v75 offset:16384
	ds_read_b64 v[180:181], v76 offset:16384
	ds_read_b64 v[182:183], v77 offset:16384
	ds_read_b64 v[184:185], v78 offset:16384
	ds_read_b64 v[186:187], v79 offset:16384
	ds_read_b64 v[188:189], v80 offset:16384
	ds_read_b64 v[190:191], v81 offset:16384
	ds_read_b64 v[192:193], v82 offset:16384
	ds_read_b64 v[194:195], v83 offset:16384
	ds_read_b64 v[196:197], v84 offset:16384
	ds_read_b64 v[198:199], v85 offset:16384
	ds_read_b64 v[200:201], v86 offset:16384
	ds_read_b64 v[202:203], v87 offset:16384
	v_cvt_pk_bf16_f32 v97, v92, v93
	s_setprio 1
	v_mov_b32_e32 v92, v90
	v_mov_b32_e32 v93, v91
	v_mov_b32_e32 v100, v98
	v_mov_b32_e32 v101, v99
	v_mov_b32_e32 v108, v106
	v_mfma_f32_16x16x32_bf16 v[204:207], v[92:95], v[6:9], 0
	v_mov_b32_e32 v109, v107
	v_mov_b32_e32 v116, v114
	v_mov_b32_e32 v117, v115
	v_mfma_f32_16x16x32_bf16 v[90:93], v[92:95], v[22:25], 0
	v_mov_b32_e32 v124, v122
	v_mov_b32_e32 v125, v123
	v_mov_b32_e32 v132, v130
	v_mfma_f32_16x16x32_bf16 v[204:207], v[100:103], v[10:13], v[204:207]
	v_mov_b32_e32 v133, v131
	v_mov_b32_e32 v160, v158
	v_mov_b32_e32 v161, v159
	v_mfma_f32_16x16x32_bf16 v[90:93], v[100:103], v[26:29], v[90:93]
	v_mov_b32_e32 v168, v166
	v_mov_b32_e32 v169, v167
	v_mfma_f32_16x16x32_bf16 v[98:101], v[108:111], v[14:17], v[204:207]
	v_mfma_f32_16x16x32_bf16 v[90:93], v[108:111], v[30:33], v[90:93]
	v_mfma_f32_16x16x32_bf16 v[98:101], v[116:119], v[18:21], v[98:101]
	v_mfma_f32_16x16x32_bf16 v[90:93], v[116:119], v[34:37], v[90:93]
	v_mfma_f32_16x16x32_bf16 v[98:101], v[124:127], v[38:41], v[98:101]
	v_mfma_f32_16x16x32_bf16 v[90:93], v[124:127], v[54:57], v[90:93]
	v_mfma_f32_16x16x32_bf16 v[98:101], v[132:135], v[42:45], v[98:101]
	v_mfma_f32_16x16x32_bf16 v[90:93], v[132:135], v[58:61], v[90:93]
	v_mfma_f32_16x16x32_bf16 v[98:101], v[160:163], v[46:49], v[98:101]
	v_mfma_f32_16x16x32_bf16 v[90:93], v[160:163], v[62:65], v[90:93]
	v_mfma_f32_16x16x32_bf16 v[98:101], v[168:171], v[50:53], v[98:101]
	v_mfma_f32_16x16x32_bf16 v[92:95], v[168:171], v[66:69], v[90:93]
	s_setprio 0
	s_nop 5
	v_mul_f32_e32 v90, v5, v98
	v_mul_f32_e32 v91, v5, v99
	v_cvt_pk_bf16_f32 v90, v90, v91
	v_mul_f32_e32 v91, v5, v100
	v_mul_f32_e32 v98, v5, v101
	v_mul_f32_e32 v92, v136, v92
	v_cvt_pk_bf16_f32 v91, v91, v98
	v_mul_f32_e32 v93, v136, v93
	v_cvt_pk_bf16_f32 v98, v92, v93
	v_mul_f32_e32 v92, v136, v94
	s_mov_b32 s2, 0xae00000
	v_mul_f32_e32 v93, v136, v95
	v_cvt_pk_bf16_f32 v99, v92, v93
	v_add_co_u32_e32 v92, vcc, s2, v70
	s_mov_b32 s2, 0xae08000
	s_nop 0
	v_addc_co_u32_e32 v93, vcc, 0, v71, vcc
	v_add_co_u32_e32 v134, vcc, s2, v70
	global_store_dwordx4 v[92:93], v[88:91], off sc1
	s_nop 0
	v_addc_co_u32_e32 v135, vcc, 0, v71, vcc
	global_store_dwordx4 v[134:135], v[96:99], off sc1
	ds_read_b64 v[88:89], v72 offset:18432
	ds_read_b64 v[90:91], v73 offset:18432
	ds_read_b64 v[92:93], v74 offset:18432
	ds_read_b64 v[94:95], v75 offset:18432
	ds_read_b64 v[96:97], v76 offset:18432
	ds_read_b64 v[98:99], v77 offset:18432
	ds_read_b64 v[100:101], v78 offset:18432
	ds_read_b64 v[102:103], v79 offset:18432
	ds_read_b64 v[104:105], v80 offset:18432
	ds_read_b64 v[106:107], v81 offset:18432
	ds_read_b64 v[108:109], v82 offset:18432
	ds_read_b64 v[110:111], v83 offset:18432
	ds_read_b64 v[112:113], v84 offset:18432
	ds_read_b64 v[114:115], v85 offset:18432
	ds_read_b64 v[116:117], v86 offset:18432
	ds_read_b64 v[118:119], v87 offset:18432
	s_setprio 1
	s_waitcnt lgkmcnt(14)
	v_mfma_f32_16x16x32_bf16 v[120:123], v[172:175], v[6:9], 0
	v_mfma_f32_16x16x32_bf16 v[124:127], v[172:175], v[22:25], 0
	v_mfma_f32_16x16x32_bf16 v[120:123], v[176:179], v[10:13], v[120:123]
	v_mfma_f32_16x16x32_bf16 v[124:127], v[176:179], v[26:29], v[124:127]
	v_mfma_f32_16x16x32_bf16 v[120:123], v[180:183], v[14:17], v[120:123]
	v_mfma_f32_16x16x32_bf16 v[124:127], v[180:183], v[30:33], v[124:127]
	v_mfma_f32_16x16x32_bf16 v[120:123], v[184:187], v[18:21], v[120:123]
	v_mfma_f32_16x16x32_bf16 v[124:127], v[184:187], v[34:37], v[124:127]
	v_mfma_f32_16x16x32_bf16 v[120:123], v[188:191], v[38:41], v[120:123]
	v_mfma_f32_16x16x32_bf16 v[124:127], v[188:191], v[54:57], v[124:127]
	v_mfma_f32_16x16x32_bf16 v[120:123], v[192:195], v[42:45], v[120:123]
	v_mfma_f32_16x16x32_bf16 v[124:127], v[192:195], v[58:61], v[124:127]
	v_mfma_f32_16x16x32_bf16 v[120:123], v[196:199], v[46:49], v[120:123]
	v_mfma_f32_16x16x32_bf16 v[124:127], v[196:199], v[62:65], v[124:127]
	v_mfma_f32_16x16x32_bf16 v[120:123], v[200:203], v[50:53], v[120:123]
	v_mfma_f32_16x16x32_bf16 v[124:127], v[200:203], v[66:69], v[124:127]
	s_setprio 0
	ds_read_b64 v[128:129], v72 offset:32768
	ds_read_b64 v[130:131], v73 offset:32768
	ds_read_b64 v[156:157], v74 offset:32768
	ds_read_b64 v[158:159], v75 offset:32768
	ds_read_b64 v[160:161], v76 offset:32768
	ds_read_b64 v[162:163], v77 offset:32768
	ds_read_b64 v[164:165], v78 offset:32768
	ds_read_b64 v[166:167], v79 offset:32768
	ds_read_b64 v[168:169], v80 offset:32768
	ds_read_b64 v[170:171], v81 offset:32768
	ds_read_b64 v[172:173], v82 offset:32768
	ds_read_b64 v[174:175], v83 offset:32768
	ds_read_b64 v[176:177], v84 offset:32768
	ds_read_b64 v[178:179], v85 offset:32768
	ds_read_b64 v[180:181], v86 offset:32768
	ds_read_b64 v[182:183], v87 offset:32768
	v_mul_f32_e32 v70, v5, v120
	v_mul_f32_e32 v71, v5, v121
	v_cvt_pk_bf16_f32 v120, v70, v71
	v_mul_f32_e32 v70, v5, v122
	v_mul_f32_e32 v71, v5, v123
	v_cvt_pk_bf16_f32 v121, v70, v71
	v_mul_f32_e32 v70, v136, v124
	v_mul_f32_e32 v71, v136, v125
	v_cvt_pk_bf16_f32 v124, v70, v71
	v_mul_f32_e32 v70, v136, v126
	v_mul_f32_e32 v71, v136, v127
	v_cvt_pk_bf16_f32 v125, v70, v71
	s_setprio 1
	v_mfma_f32_16x16x32_bf16 v[184:187], v[88:91], v[6:9], 0
	v_mfma_f32_16x16x32_bf16 v[88:91], v[88:91], v[22:25], 0
	s_waitcnt lgkmcnt(14)
	v_mfma_f32_16x16x32_bf16 v[184:187], v[92:95], v[10:13], v[184:187]
	v_mfma_f32_16x16x32_bf16 v[88:91], v[92:95], v[26:29], v[88:91]
	v_mfma_f32_16x16x32_bf16 v[92:95], v[96:99], v[14:17], v[184:187]
	v_mfma_f32_16x16x32_bf16 v[88:91], v[96:99], v[30:33], v[88:91]
	v_mfma_f32_16x16x32_bf16 v[92:95], v[100:103], v[18:21], v[92:95]
	v_mfma_f32_16x16x32_bf16 v[88:91], v[100:103], v[34:37], v[88:91]
	v_mfma_f32_16x16x32_bf16 v[92:95], v[104:107], v[38:41], v[92:95]
	v_mfma_f32_16x16x32_bf16 v[88:91], v[104:107], v[54:57], v[88:91]
	v_mfma_f32_16x16x32_bf16 v[92:95], v[108:111], v[42:45], v[92:95]
	v_mfma_f32_16x16x32_bf16 v[88:91], v[108:111], v[58:61], v[88:91]
	v_mfma_f32_16x16x32_bf16 v[92:95], v[112:115], v[46:49], v[92:95]
	v_mfma_f32_16x16x32_bf16 v[88:91], v[112:115], v[62:65], v[88:91]
	v_mfma_f32_16x16x32_bf16 v[92:95], v[116:119], v[50:53], v[92:95]
	v_mfma_f32_16x16x32_bf16 v[88:91], v[116:119], v[66:69], v[88:91]
	s_setprio 0
	s_nop 5
	v_mul_f32_e32 v70, v5, v92
	v_mul_f32_e32 v71, v5, v93
	v_cvt_pk_bf16_f32 v122, v70, v71
	v_mul_f32_e32 v70, v5, v94
	v_mul_f32_e32 v71, v5, v95
	v_cvt_pk_bf16_f32 v123, v70, v71
	v_mul_f32_e32 v70, v136, v88
	v_mul_f32_e32 v71, v136, v89
	v_cvt_pk_bf16_f32 v126, v70, v71
	v_mul_f32_e32 v70, v136, v90
	v_mul_f32_e32 v71, v136, v91
	v_cvt_pk_bf16_f32 v127, v70, v71
	global_store_dwordx4 v[2:3], v[120:123], off offset:64 sc1
	global_store_dwordx4 v[134:135], v[124:127], off offset:64 sc1
	ds_read_b64 v[88:89], v72 offset:34816
	ds_read_b64 v[90:91], v73 offset:34816
	ds_read_b64 v[92:93], v74 offset:34816
	ds_read_b64 v[94:95], v75 offset:34816
	ds_read_b64 v[96:97], v76 offset:34816
	ds_read_b64 v[98:99], v77 offset:34816
	ds_read_b64 v[100:101], v78 offset:34816
	ds_read_b64 v[102:103], v79 offset:34816
	ds_read_b64 v[104:105], v80 offset:34816
	ds_read_b64 v[106:107], v81 offset:34816
	ds_read_b64 v[108:109], v82 offset:34816
	ds_read_b64 v[110:111], v83 offset:34816
	ds_read_b64 v[112:113], v84 offset:34816
	ds_read_b64 v[114:115], v85 offset:34816
	ds_read_b64 v[116:117], v86 offset:34816
	ds_read_b64 v[118:119], v87 offset:34816
	s_setprio 1
	v_mfma_f32_16x16x32_bf16 v[120:123], v[128:131], v[6:9], 0
	v_mfma_f32_16x16x32_bf16 v[124:127], v[128:131], v[22:25], 0
	s_waitcnt lgkmcnt(14)
	v_mfma_f32_16x16x32_bf16 v[120:123], v[156:159], v[10:13], v[120:123]
	v_mfma_f32_16x16x32_bf16 v[124:127], v[156:159], v[26:29], v[124:127]
	v_mfma_f32_16x16x32_bf16 v[120:123], v[160:163], v[14:17], v[120:123]
	v_mfma_f32_16x16x32_bf16 v[124:127], v[160:163], v[30:33], v[124:127]
	v_mfma_f32_16x16x32_bf16 v[120:123], v[164:167], v[18:21], v[120:123]
	v_mfma_f32_16x16x32_bf16 v[124:127], v[164:167], v[34:37], v[124:127]
	v_mfma_f32_16x16x32_bf16 v[120:123], v[168:171], v[38:41], v[120:123]
	v_mfma_f32_16x16x32_bf16 v[124:127], v[168:171], v[54:57], v[124:127]
	v_mfma_f32_16x16x32_bf16 v[120:123], v[172:175], v[42:45], v[120:123]
	v_mfma_f32_16x16x32_bf16 v[124:127], v[172:175], v[58:61], v[124:127]
	v_mfma_f32_16x16x32_bf16 v[120:123], v[176:179], v[46:49], v[120:123]
	v_mfma_f32_16x16x32_bf16 v[124:127], v[176:179], v[62:65], v[124:127]
	v_mfma_f32_16x16x32_bf16 v[120:123], v[180:183], v[50:53], v[120:123]
	v_mfma_f32_16x16x32_bf16 v[124:127], v[180:183], v[66:69], v[124:127]
	s_setprio 0
	ds_read_b64 v[128:129], v72 offset:49152
	ds_read_b64 v[130:131], v73 offset:49152
	ds_read_b64 v[156:157], v74 offset:49152
	ds_read_b64 v[158:159], v75 offset:49152
	ds_read_b64 v[160:161], v76 offset:49152
	ds_read_b64 v[162:163], v77 offset:49152
	ds_read_b64 v[164:165], v78 offset:49152
	ds_read_b64 v[166:167], v79 offset:49152
	ds_read_b64 v[168:169], v80 offset:49152
	ds_read_b64 v[170:171], v81 offset:49152
	ds_read_b64 v[172:173], v82 offset:49152
	ds_read_b64 v[174:175], v83 offset:49152
	ds_read_b64 v[176:177], v84 offset:49152
	ds_read_b64 v[178:179], v85 offset:49152
	ds_read_b64 v[180:181], v86 offset:49152
	ds_read_b64 v[182:183], v87 offset:49152
	v_mul_f32_e32 v70, v5, v120
	v_mul_f32_e32 v71, v5, v121
	v_cvt_pk_bf16_f32 v120, v70, v71
	v_mul_f32_e32 v70, v5, v122
	v_mul_f32_e32 v71, v5, v123
	v_cvt_pk_bf16_f32 v121, v70, v71
	v_mul_f32_e32 v70, v136, v124
	v_mul_f32_e32 v71, v136, v125
	v_cvt_pk_bf16_f32 v124, v70, v71
	v_mul_f32_e32 v70, v136, v126
	v_mul_f32_e32 v71, v136, v127
	v_cvt_pk_bf16_f32 v125, v70, v71
	s_setprio 1
	v_mfma_f32_16x16x32_bf16 v[184:187], v[88:91], v[6:9], 0
	v_mfma_f32_16x16x32_bf16 v[88:91], v[88:91], v[22:25], 0
	s_waitcnt lgkmcnt(14)
	v_mfma_f32_16x16x32_bf16 v[184:187], v[92:95], v[10:13], v[184:187]
	v_mfma_f32_16x16x32_bf16 v[88:91], v[92:95], v[26:29], v[88:91]
	v_mfma_f32_16x16x32_bf16 v[92:95], v[96:99], v[14:17], v[184:187]
	v_mfma_f32_16x16x32_bf16 v[88:91], v[96:99], v[30:33], v[88:91]
	v_mfma_f32_16x16x32_bf16 v[92:95], v[100:103], v[18:21], v[92:95]
	v_mfma_f32_16x16x32_bf16 v[88:91], v[100:103], v[34:37], v[88:91]
	v_mfma_f32_16x16x32_bf16 v[92:95], v[104:107], v[38:41], v[92:95]
	v_mfma_f32_16x16x32_bf16 v[88:91], v[104:107], v[54:57], v[88:91]
	v_mfma_f32_16x16x32_bf16 v[92:95], v[108:111], v[42:45], v[92:95]
	v_mfma_f32_16x16x32_bf16 v[88:91], v[108:111], v[58:61], v[88:91]
	v_mfma_f32_16x16x32_bf16 v[92:95], v[112:115], v[46:49], v[92:95]
	v_mfma_f32_16x16x32_bf16 v[88:91], v[112:115], v[62:65], v[88:91]
	v_mfma_f32_16x16x32_bf16 v[92:95], v[116:119], v[50:53], v[92:95]
	v_mfma_f32_16x16x32_bf16 v[88:91], v[116:119], v[66:69], v[88:91]
	s_setprio 0
	s_nop 5
	v_mul_f32_e32 v70, v5, v92
	v_mul_f32_e32 v71, v5, v93
	v_cvt_pk_bf16_f32 v122, v70, v71
	v_mul_f32_e32 v70, v5, v94
	v_mul_f32_e32 v71, v5, v95
	v_cvt_pk_bf16_f32 v123, v70, v71
	v_mul_f32_e32 v70, v136, v88
	v_mul_f32_e32 v71, v136, v89
	v_cvt_pk_bf16_f32 v126, v70, v71
	v_mul_f32_e32 v70, v136, v90
	v_mul_f32_e32 v71, v136, v91
	v_cvt_pk_bf16_f32 v127, v70, v71
	global_store_dwordx4 v[2:3], v[120:123], off offset:128 sc1
	global_store_dwordx4 v[134:135], v[124:127], off offset:128 sc1
	ds_read_b64 v[70:71], v72 offset:51200
	ds_read_b64 v[72:73], v73 offset:51200
	ds_read_b64 v[88:89], v74 offset:51200
	ds_read_b64 v[90:91], v75 offset:51200
	ds_read_b64 v[74:75], v76 offset:51200
	ds_read_b64 v[76:77], v77 offset:51200
	ds_read_b64 v[92:93], v78 offset:51200
	ds_read_b64 v[94:95], v79 offset:51200
	ds_read_b64 v[78:79], v80 offset:51200
	ds_read_b64 v[80:81], v81 offset:51200
	ds_read_b64 v[96:97], v82 offset:51200
	ds_read_b64 v[98:99], v83 offset:51200
	ds_read_b64 v[82:83], v84 offset:51200
	ds_read_b64 v[84:85], v85 offset:51200
	ds_read_b64 v[100:101], v86 offset:51200
	ds_read_b64 v[102:103], v87 offset:51200
	s_setprio 1
	v_mfma_f32_16x16x32_bf16 v[104:107], v[128:131], v[6:9], 0
	v_mfma_f32_16x16x32_bf16 v[108:111], v[128:131], v[22:25], 0
	s_waitcnt lgkmcnt(14)
	v_mfma_f32_16x16x32_bf16 v[104:107], v[156:159], v[10:13], v[104:107]
	v_mfma_f32_16x16x32_bf16 v[108:111], v[156:159], v[26:29], v[108:111]
	v_mfma_f32_16x16x32_bf16 v[104:107], v[160:163], v[14:17], v[104:107]
	v_mfma_f32_16x16x32_bf16 v[108:111], v[160:163], v[30:33], v[108:111]
	v_mfma_f32_16x16x32_bf16 v[104:107], v[164:167], v[18:21], v[104:107]
	v_mfma_f32_16x16x32_bf16 v[108:111], v[164:167], v[34:37], v[108:111]
	v_mfma_f32_16x16x32_bf16 v[104:107], v[168:171], v[38:41], v[104:107]
	v_mfma_f32_16x16x32_bf16 v[108:111], v[168:171], v[54:57], v[108:111]
	v_mfma_f32_16x16x32_bf16 v[104:107], v[172:175], v[42:45], v[104:107]
	v_mfma_f32_16x16x32_bf16 v[108:111], v[172:175], v[58:61], v[108:111]
	v_mfma_f32_16x16x32_bf16 v[104:107], v[176:179], v[46:49], v[104:107]
	v_mfma_f32_16x16x32_bf16 v[108:111], v[176:179], v[62:65], v[108:111]
	v_mfma_f32_16x16x32_bf16 v[104:107], v[180:183], v[50:53], v[104:107]
	v_mfma_f32_16x16x32_bf16 v[108:111], v[180:183], v[66:69], v[108:111]
	s_setprio 0
	s_nop 5
	v_mul_f32_e32 v86, v5, v104
	v_mul_f32_e32 v87, v5, v105
	v_cvt_pk_bf16_f32 v86, v86, v87
	v_mul_f32_e32 v87, v5, v106
	v_mul_f32_e32 v104, v5, v107
	v_cvt_pk_bf16_f32 v87, v87, v104
	v_mul_f32_e32 v104, v136, v108
	v_mul_f32_e32 v105, v136, v109
	v_cvt_pk_bf16_f32 v104, v104, v105
	v_mul_f32_e32 v105, v136, v110
	v_mul_f32_e32 v106, v136, v111
	v_cvt_pk_bf16_f32 v105, v105, v106
	s_setprio 1
	v_mfma_f32_16x16x32_bf16 v[106:109], v[70:73], v[6:9], 0
	v_mfma_f32_16x16x32_bf16 v[70:73], v[70:73], v[22:25], 0
	s_waitcnt lgkmcnt(12)
	v_mfma_f32_16x16x32_bf16 v[106:109], v[88:91], v[10:13], v[106:109]
	v_mfma_f32_16x16x32_bf16 v[70:73], v[88:91], v[26:29], v[70:73]
	s_waitcnt lgkmcnt(10)
	v_mfma_f32_16x16x32_bf16 v[88:91], v[74:77], v[14:17], v[106:109]
	v_mfma_f32_16x16x32_bf16 v[70:73], v[74:77], v[30:33], v[70:73]
	s_waitcnt lgkmcnt(8)
	v_mfma_f32_16x16x32_bf16 v[74:77], v[92:95], v[18:21], v[88:91]
	v_mfma_f32_16x16x32_bf16 v[70:73], v[92:95], v[34:37], v[70:73]
	s_waitcnt lgkmcnt(6)
	v_mfma_f32_16x16x32_bf16 v[74:77], v[78:81], v[38:41], v[74:77]
	v_mfma_f32_16x16x32_bf16 v[70:73], v[78:81], v[54:57], v[70:73]
	s_waitcnt lgkmcnt(4)
	v_mfma_f32_16x16x32_bf16 v[74:77], v[96:99], v[42:45], v[74:77]
	v_mfma_f32_16x16x32_bf16 v[70:73], v[96:99], v[58:61], v[70:73]
	s_waitcnt lgkmcnt(2)
	v_mfma_f32_16x16x32_bf16 v[74:77], v[82:85], v[46:49], v[74:77]
	v_mfma_f32_16x16x32_bf16 v[70:73], v[82:85], v[62:65], v[70:73]
	s_waitcnt lgkmcnt(0)
	v_mfma_f32_16x16x32_bf16 v[74:77], v[100:103], v[50:53], v[74:77]
	v_mfma_f32_16x16x32_bf16 v[70:73], v[100:103], v[66:69], v[70:73]
	s_setprio 0
	s_nop 5
	v_mul_f32_e32 v74, v5, v74
	v_mul_f32_e32 v75, v5, v75
	v_mul_f32_e32 v70, v136, v70
	v_cvt_pk_bf16_f32 v88, v74, v75
	v_mul_f32_e32 v74, v5, v76
	v_mul_f32_e32 v75, v5, v77
	v_cvt_pk_bf16_f32 v89, v74, v75
	v_mul_f32_e32 v71, v136, v71
	v_cvt_pk_bf16_f32 v106, v70, v71
	v_mul_f32_e32 v70, v136, v72
	v_add_u32_e32 v78, 0x10000, v146
	v_mul_f32_e32 v71, v136, v73
	v_cvt_pk_bf16_f32 v107, v70, v71
	global_store_dwordx4 v[2:3], v[86:89], off offset:192 sc1
	global_store_dwordx4 v[134:135], v[104:107], off offset:192 sc1
	v_add_u32_e32 v70, v78, v149
	v_add_u32_e32 v72, v78, v151
	v_add_u32_e32 v74, v78, v153
	v_add_u32_e32 v76, v78, v154
	v_add_u32_e32 v79, v78, v143
	v_add_u32_e32 v80, v78, v147
	v_add_u32_e32 v81, v78, v150
	s_waitcnt vmcnt(8)
	s_barrier
	ds_read_b64 v[70:71], v70
	ds_read_b64 v[72:73], v72
	ds_read_b64 v[74:75], v74
	ds_read_b64 v[76:77], v76
	v_add_u32_e32 v86, v78, v152
	ds_read_b64 v[82:83], v79
	ds_read_b64 v[84:85], v80
	ds_read_b64 v[90:91], v81
	ds_read_b64 v[92:93], v86
	v_add_u32_e32 v79, v78, v139
	v_add_u32_e32 v80, v78, v141
	v_add_u32_e32 v81, v78, v145
	v_add_u32_e32 v86, v78, v148
	ds_read_b64 v[94:95], v79
	ds_read_b64 v[96:97], v80
	ds_read_b64 v[98:99], v81
	ds_read_b64 v[100:101], v86
	v_add_u32_e32 v79, v78, v137
	v_add_u32_e32 v80, v78, v138
	v_add_u32_e32 v81, v78, v140
	v_add_u32_e32 v78, v78, v142
	ds_read_b64 v[102:103], v79
	ds_read_b64 v[104:105], v80
	ds_read_b64 v[106:107], v81
	ds_read_b64 v[108:109], v78
	v_add_u32_e32 v78, 0x10800, v146
	v_add_u32_e32 v79, v78, v149
	v_add_u32_e32 v80, v78, v151
	v_add_u32_e32 v81, v78, v153
	v_add_u32_e32 v86, v78, v154
	ds_read_b64 v[110:111], v79
	ds_read_b64 v[112:113], v80
	ds_read_b64 v[118:119], v81
	ds_read_b64 v[120:121], v86
	v_add_u32_e32 v79, v78, v143
	v_add_u32_e32 v80, v78, v147
	v_add_u32_e32 v81, v78, v150
	v_add_u32_e32 v86, v78, v152
	ds_read_b64 v[126:127], v79
	ds_read_b64 v[128:129], v80
	ds_read_b64 v[130:131], v81
	ds_read_b64 v[132:133], v86
	v_add_u32_e32 v79, v78, v139
	v_add_u32_e32 v80, v78, v141
	v_add_u32_e32 v81, v78, v145
	v_add_u32_e32 v88, v78, v148
	ds_read_b64 v[156:157], v79
	ds_read_b64 v[158:159], v80
	ds_read_b64 v[86:87], v81
	ds_read_b64 v[88:89], v88
	v_add_u32_e32 v79, v78, v137
	v_add_u32_e32 v80, v78, v138
	v_add_u32_e32 v81, v78, v140
	v_add_u32_e32 v114, v78, v142
	ds_read_b64 v[160:161], v79
	ds_read_b64 v[162:163], v80
	ds_read_b64 v[78:79], v81
	ds_read_b64 v[80:81], v114
	s_setprio 1
	s_waitcnt lgkmcnt(14)
	v_mfma_f32_16x16x32_bf16 v[114:117], v[70:73], v[6:9], 0
	v_mfma_f32_16x16x32_bf16 v[70:73], v[70:73], v[22:25], 0
	v_mfma_f32_16x16x32_bf16 v[114:117], v[74:77], v[10:13], v[114:117]
	v_mfma_f32_16x16x32_bf16 v[70:73], v[74:77], v[26:29], v[70:73]
	v_mfma_f32_16x16x32_bf16 v[74:77], v[82:85], v[14:17], v[114:117]
	v_mfma_f32_16x16x32_bf16 v[70:73], v[82:85], v[30:33], v[70:73]
	v_mfma_f32_16x16x32_bf16 v[74:77], v[90:93], v[18:21], v[74:77]
	v_mfma_f32_16x16x32_bf16 v[70:73], v[90:93], v[34:37], v[70:73]
	v_mfma_f32_16x16x32_bf16 v[74:77], v[94:97], v[38:41], v[74:77]
	v_mfma_f32_16x16x32_bf16 v[70:73], v[94:97], v[54:57], v[70:73]
	v_mfma_f32_16x16x32_bf16 v[74:77], v[98:101], v[42:45], v[74:77]
	v_mfma_f32_16x16x32_bf16 v[70:73], v[98:101], v[58:61], v[70:73]
	v_mfma_f32_16x16x32_bf16 v[74:77], v[102:105], v[46:49], v[74:77]
	v_mfma_f32_16x16x32_bf16 v[70:73], v[102:105], v[62:65], v[70:73]
	v_mfma_f32_16x16x32_bf16 v[74:77], v[106:109], v[50:53], v[74:77]
	v_mfma_f32_16x16x32_bf16 v[70:73], v[106:109], v[66:69], v[70:73]
	s_setprio 0
	v_add_u32_e32 v96, 0x14000, v146
	v_add_u32_e32 v97, v96, v139
	ds_read_b64 v[98:99], v97
	v_add_u32_e32 v97, v96, v141
	ds_read_b64 v[100:101], v97
	v_add_u32_e32 v97, v96, v145
	ds_read_b64 v[106:107], v97
	v_add_u32_e32 v97, v96, v148
	v_mul_f32_e32 v74, v5, v74
	v_mul_f32_e32 v70, v136, v70
	ds_read_b64 v[108:109], v97
	v_add_u32_e32 v97, v96, v137
	v_mul_f32_e32 v75, v5, v75
	v_cvt_pk_bf16_f32 v94, v74, v75
	v_mul_f32_e32 v74, v5, v76
	v_mul_f32_e32 v71, v136, v71
	v_cvt_pk_bf16_f32 v102, v70, v71
	v_mul_f32_e32 v70, v136, v72
	ds_read_b64 v[114:115], v97
	v_add_u32_e32 v97, v96, v138
	v_mul_f32_e32 v75, v5, v77
	v_cvt_pk_bf16_f32 v95, v74, v75
	v_mul_f32_e32 v71, v136, v73
	v_cvt_pk_bf16_f32 v103, v70, v71
	v_add_u32_e32 v70, v96, v149
	v_add_u32_e32 v72, v96, v151
	v_add_u32_e32 v74, v96, v153
	v_add_u32_e32 v76, v96, v154
	v_add_u32_e32 v82, v96, v143
	v_add_u32_e32 v84, v96, v147
	v_add_u32_e32 v90, v96, v150
	v_add_u32_e32 v92, v96, v152
	ds_read_b64 v[116:117], v97
	v_add_u32_e32 v97, v96, v140
	v_add_u32_e32 v96, v96, v142
	ds_read_b64 v[70:71], v70
	ds_read_b64 v[72:73], v72
	ds_read_b64 v[74:75], v74
	ds_read_b64 v[76:77], v76
	ds_read_b64 v[82:83], v82
	ds_read_b64 v[84:85], v84
	ds_read_b64 v[90:91], v90
	ds_read_b64 v[92:93], v92
	ds_read_b64 v[122:123], v97
	ds_read_b64 v[124:125], v96
	s_setprio 1
	v_mfma_f32_16x16x32_bf16 v[164:167], v[110:113], v[6:9], 0
	v_mfma_f32_16x16x32_bf16 v[110:113], v[110:113], v[22:25], 0
	s_waitcnt lgkmcnt(14)
	v_mfma_f32_16x16x32_bf16 v[164:167], v[118:121], v[10:13], v[164:167]
	v_mfma_f32_16x16x32_bf16 v[110:113], v[118:121], v[26:29], v[110:113]
	v_mfma_f32_16x16x32_bf16 v[118:121], v[126:129], v[14:17], v[164:167]
	v_mfma_f32_16x16x32_bf16 v[110:113], v[126:129], v[30:33], v[110:113]
	v_mfma_f32_16x16x32_bf16 v[118:121], v[130:133], v[18:21], v[118:121]
	v_mfma_f32_16x16x32_bf16 v[110:113], v[130:133], v[34:37], v[110:113]
	v_mfma_f32_16x16x32_bf16 v[118:121], v[156:159], v[38:41], v[118:121]
	v_mfma_f32_16x16x32_bf16 v[110:113], v[156:159], v[54:57], v[110:113]
	v_mfma_f32_16x16x32_bf16 v[118:121], v[86:89], v[42:45], v[118:121]
	v_mfma_f32_16x16x32_bf16 v[86:89], v[86:89], v[58:61], v[110:113]
	v_mfma_f32_16x16x32_bf16 v[110:113], v[160:163], v[46:49], v[118:121]
	v_mfma_f32_16x16x32_bf16 v[86:89], v[160:163], v[62:65], v[86:89]
	v_mfma_f32_16x16x32_bf16 v[110:113], v[78:81], v[50:53], v[110:113]
	v_mfma_f32_16x16x32_bf16 v[78:81], v[78:81], v[66:69], v[86:89]
	s_setprio 0
	s_nop 5
	v_mul_f32_e32 v86, v5, v110
	v_mul_f32_e32 v87, v5, v111
	v_mul_f32_e32 v78, v136, v78
	v_cvt_pk_bf16_f32 v96, v86, v87
	v_mul_f32_e32 v86, v5, v112
	v_mul_f32_e32 v87, v5, v113
	v_cvt_pk_bf16_f32 v97, v86, v87
	v_mul_f32_e32 v79, v136, v79
	v_cvt_pk_bf16_f32 v104, v78, v79
	v_mul_f32_e32 v78, v136, v80
	v_add_u32_e32 v132, 0x14800, v146
	v_mul_f32_e32 v79, v136, v81
	v_cvt_pk_bf16_f32 v105, v78, v79
	global_store_dwordx4 v[2:3], v[94:97], off offset:256 sc1
	global_store_dwordx4 v[134:135], v[102:105], off offset:256 sc1
	v_add_u32_e32 v78, v132, v149
	v_add_u32_e32 v80, v132, v151
	v_add_u32_e32 v86, v132, v153
	v_add_u32_e32 v88, v132, v154
	v_add_u32_e32 v94, v132, v143
	v_add_u32_e32 v96, v132, v147
	v_add_u32_e32 v102, v132, v150
	v_add_u32_e32 v104, v132, v152
	v_add_u32_e32 v110, v132, v139
	v_add_u32_e32 v112, v132, v141
	v_add_u32_e32 v118, v132, v145
	v_add_u32_e32 v120, v132, v148
	v_add_u32_e32 v126, v132, v137
	v_add_u32_e32 v128, v132, v138
	v_add_u32_e32 v130, v132, v140
	v_add_u32_e32 v132, v132, v142
	ds_read_b64 v[78:79], v78
	ds_read_b64 v[80:81], v80
	ds_read_b64 v[86:87], v86
	ds_read_b64 v[88:89], v88
	ds_read_b64 v[94:95], v94
	ds_read_b64 v[96:97], v96
	ds_read_b64 v[102:103], v102
	ds_read_b64 v[104:105], v104
	ds_read_b64 v[110:111], v110
	ds_read_b64 v[112:113], v112
	ds_read_b64 v[118:119], v118
	ds_read_b64 v[120:121], v120
	ds_read_b64 v[126:127], v126
	ds_read_b64 v[128:129], v128
	ds_read_b64 v[130:131], v130
	ds_read_b64 v[132:133], v132
	s_setprio 1
	s_waitcnt lgkmcnt(14)
	v_mfma_f32_16x16x32_bf16 v[156:159], v[70:73], v[6:9], 0
	v_mfma_f32_16x16x32_bf16 v[70:73], v[70:73], v[22:25], 0
	v_mfma_f32_16x16x32_bf16 v[156:159], v[74:77], v[10:13], v[156:159]
	v_mfma_f32_16x16x32_bf16 v[70:73], v[74:77], v[26:29], v[70:73]
	v_mfma_f32_16x16x32_bf16 v[74:77], v[82:85], v[14:17], v[156:159]
	v_mfma_f32_16x16x32_bf16 v[70:73], v[82:85], v[30:33], v[70:73]
	v_mfma_f32_16x16x32_bf16 v[74:77], v[90:93], v[18:21], v[74:77]
	v_mfma_f32_16x16x32_bf16 v[70:73], v[90:93], v[34:37], v[70:73]
	v_mfma_f32_16x16x32_bf16 v[74:77], v[98:101], v[38:41], v[74:77]
	v_mfma_f32_16x16x32_bf16 v[70:73], v[98:101], v[54:57], v[70:73]
	v_mfma_f32_16x16x32_bf16 v[74:77], v[106:109], v[42:45], v[74:77]
	v_mfma_f32_16x16x32_bf16 v[70:73], v[106:109], v[58:61], v[70:73]
	v_mfma_f32_16x16x32_bf16 v[74:77], v[114:117], v[46:49], v[74:77]
	v_mfma_f32_16x16x32_bf16 v[70:73], v[114:117], v[62:65], v[70:73]
	v_mfma_f32_16x16x32_bf16 v[74:77], v[122:125], v[50:53], v[74:77]
	v_mfma_f32_16x16x32_bf16 v[70:73], v[122:125], v[66:69], v[70:73]
	s_setprio 0
	s_nop 5
	v_mul_f32_e32 v74, v5, v74
	v_mul_f32_e32 v70, v136, v70
	v_mul_f32_e32 v75, v5, v75
	v_cvt_pk_bf16_f32 v156, v74, v75
	v_mul_f32_e32 v74, v5, v76
	v_mul_f32_e32 v71, v136, v71
	v_cvt_pk_bf16_f32 v160, v70, v71
	v_mul_f32_e32 v70, v136, v72
	v_add_u32_e32 v124, 0x18000, v146
	v_mul_f32_e32 v75, v5, v77
	v_cvt_pk_bf16_f32 v157, v74, v75
	v_mul_f32_e32 v71, v136, v73
	v_cvt_pk_bf16_f32 v161, v70, v71
	v_add_u32_e32 v70, v124, v149
	v_add_u32_e32 v72, v124, v151
	v_add_u32_e32 v74, v124, v153
	v_add_u32_e32 v76, v124, v154
	v_add_u32_e32 v82, v124, v143
	v_add_u32_e32 v84, v124, v147
	v_add_u32_e32 v90, v124, v150
	v_add_u32_e32 v92, v124, v152
	v_add_u32_e32 v98, v124, v139
	v_add_u32_e32 v100, v124, v141
	v_add_u32_e32 v106, v124, v145
	v_add_u32_e32 v108, v124, v148
	v_add_u32_e32 v114, v124, v137
	v_add_u32_e32 v116, v124, v138
	v_add_u32_e32 v122, v124, v140
	v_add_u32_e32 v124, v124, v142
	ds_read_b64 v[70:71], v70
	ds_read_b64 v[72:73], v72
	ds_read_b64 v[74:75], v74
	ds_read_b64 v[76:77], v76
	ds_read_b64 v[82:83], v82
	ds_read_b64 v[84:85], v84
	ds_read_b64 v[90:91], v90
	ds_read_b64 v[92:93], v92
	ds_read_b64 v[98:99], v98
	ds_read_b64 v[100:101], v100
	ds_read_b64 v[106:107], v106
	ds_read_b64 v[108:109], v108
	ds_read_b64 v[114:115], v114
	ds_read_b64 v[116:117], v116
	ds_read_b64 v[122:123], v122
	ds_read_b64 v[124:125], v124
	s_setprio 1
	v_mfma_f32_16x16x32_bf16 v[162:165], v[78:81], v[6:9], 0
	v_mfma_f32_16x16x32_bf16 v[78:81], v[78:81], v[22:25], 0
	s_waitcnt lgkmcnt(14)
	v_mfma_f32_16x16x32_bf16 v[162:165], v[86:89], v[10:13], v[162:165]
	v_mfma_f32_16x16x32_bf16 v[78:81], v[86:89], v[26:29], v[78:81]
	v_mfma_f32_16x16x32_bf16 v[86:89], v[94:97], v[14:17], v[162:165]
	v_mfma_f32_16x16x32_bf16 v[78:81], v[94:97], v[30:33], v[78:81]
	v_mfma_f32_16x16x32_bf16 v[86:89], v[102:105], v[18:21], v[86:89]
	v_mfma_f32_16x16x32_bf16 v[78:81], v[102:105], v[34:37], v[78:81]
	v_mfma_f32_16x16x32_bf16 v[86:89], v[110:113], v[38:41], v[86:89]
	v_mfma_f32_16x16x32_bf16 v[78:81], v[110:113], v[54:57], v[78:81]
	v_mfma_f32_16x16x32_bf16 v[86:89], v[118:121], v[42:45], v[86:89]
	v_mfma_f32_16x16x32_bf16 v[78:81], v[118:121], v[58:61], v[78:81]
	v_mfma_f32_16x16x32_bf16 v[86:89], v[126:129], v[46:49], v[86:89]
	v_mfma_f32_16x16x32_bf16 v[78:81], v[126:129], v[62:65], v[78:81]
	v_mfma_f32_16x16x32_bf16 v[86:89], v[130:133], v[50:53], v[86:89]
	v_mfma_f32_16x16x32_bf16 v[78:81], v[130:133], v[66:69], v[78:81]
	s_setprio 0
	s_nop 5
	v_mul_f32_e32 v86, v5, v86
	v_mul_f32_e32 v87, v5, v87
	v_mul_f32_e32 v78, v136, v78
	v_cvt_pk_bf16_f32 v158, v86, v87
	v_mul_f32_e32 v86, v5, v88
	v_mul_f32_e32 v87, v5, v89
	v_cvt_pk_bf16_f32 v159, v86, v87
	v_mul_f32_e32 v79, v136, v79
	v_cvt_pk_bf16_f32 v162, v78, v79
	v_mul_f32_e32 v78, v136, v80
	v_add_u32_e32 v132, 0x18800, v146
	v_mul_f32_e32 v79, v136, v81
	v_cvt_pk_bf16_f32 v163, v78, v79
	global_store_dwordx4 v[2:3], v[156:159], off offset:320 sc1
	global_store_dwordx4 v[134:135], v[160:163], off offset:320 sc1
	v_add_u32_e32 v78, v132, v149
	v_add_u32_e32 v80, v132, v151
	v_add_u32_e32 v86, v132, v153
	v_add_u32_e32 v88, v132, v154
	v_add_u32_e32 v94, v132, v143
	v_add_u32_e32 v96, v132, v147
	v_add_u32_e32 v102, v132, v150
	v_add_u32_e32 v104, v132, v152
	v_add_u32_e32 v110, v132, v139
	v_add_u32_e32 v112, v132, v141
	v_add_u32_e32 v118, v132, v145
	v_add_u32_e32 v120, v132, v148
	v_add_u32_e32 v126, v132, v137
	v_add_u32_e32 v128, v132, v138
	v_add_u32_e32 v130, v132, v140
	v_add_u32_e32 v132, v132, v142
	ds_read_b64 v[78:79], v78
	ds_read_b64 v[80:81], v80
	ds_read_b64 v[86:87], v86
	ds_read_b64 v[88:89], v88
	ds_read_b64 v[94:95], v94
	ds_read_b64 v[96:97], v96
	ds_read_b64 v[102:103], v102
	ds_read_b64 v[104:105], v104
	ds_read_b64 v[110:111], v110
	ds_read_b64 v[112:113], v112
	ds_read_b64 v[118:119], v118
	ds_read_b64 v[120:121], v120
	ds_read_b64 v[126:127], v126
	ds_read_b64 v[128:129], v128
	ds_read_b64 v[130:131], v130
	ds_read_b64 v[132:133], v132
	s_setprio 1
	v_mfma_f32_16x16x32_bf16 v[156:159], v[70:73], v[6:9], 0
	v_mfma_f32_16x16x32_bf16 v[70:73], v[70:73], v[22:25], 0
	s_waitcnt lgkmcnt(14)
	v_mfma_f32_16x16x32_bf16 v[156:159], v[74:77], v[10:13], v[156:159]
	v_mfma_f32_16x16x32_bf16 v[70:73], v[74:77], v[26:29], v[70:73]
	v_mfma_f32_16x16x32_bf16 v[74:77], v[82:85], v[14:17], v[156:159]
	v_mfma_f32_16x16x32_bf16 v[70:73], v[82:85], v[30:33], v[70:73]
	v_mfma_f32_16x16x32_bf16 v[74:77], v[90:93], v[18:21], v[74:77]
	v_mfma_f32_16x16x32_bf16 v[70:73], v[90:93], v[34:37], v[70:73]
	v_mfma_f32_16x16x32_bf16 v[74:77], v[98:101], v[38:41], v[74:77]
	v_mfma_f32_16x16x32_bf16 v[70:73], v[98:101], v[54:57], v[70:73]
	v_mfma_f32_16x16x32_bf16 v[74:77], v[106:109], v[42:45], v[74:77]
	v_mfma_f32_16x16x32_bf16 v[70:73], v[106:109], v[58:61], v[70:73]
	v_mfma_f32_16x16x32_bf16 v[74:77], v[114:117], v[46:49], v[74:77]
	v_mfma_f32_16x16x32_bf16 v[70:73], v[114:117], v[62:65], v[70:73]
	v_mfma_f32_16x16x32_bf16 v[74:77], v[122:125], v[50:53], v[74:77]
	v_mfma_f32_16x16x32_bf16 v[70:73], v[122:125], v[66:69], v[70:73]
	s_setprio 0
	s_nop 5
	v_mul_f32_e32 v74, v5, v74
	v_mul_f32_e32 v70, v136, v70
	v_mul_f32_e32 v75, v5, v75
	v_cvt_pk_bf16_f32 v156, v74, v75
	v_mul_f32_e32 v74, v5, v76
	v_mul_f32_e32 v71, v136, v71
	v_cvt_pk_bf16_f32 v160, v70, v71
	v_mul_f32_e32 v70, v136, v72
	v_add_u32_e32 v124, 0x1c000, v146
	v_mul_f32_e32 v75, v5, v77
	v_cvt_pk_bf16_f32 v157, v74, v75
	v_mul_f32_e32 v71, v136, v73
	v_cvt_pk_bf16_f32 v161, v70, v71
	v_add_u32_e32 v70, v124, v149
	v_add_u32_e32 v72, v124, v151
	v_add_u32_e32 v74, v124, v153
	v_add_u32_e32 v76, v124, v154
	v_add_u32_e32 v82, v124, v143
	v_add_u32_e32 v84, v124, v147
	v_add_u32_e32 v90, v124, v150
	v_add_u32_e32 v92, v124, v152
	v_add_u32_e32 v98, v124, v139
	v_add_u32_e32 v100, v124, v141
	v_add_u32_e32 v106, v124, v145
	v_add_u32_e32 v108, v124, v148
	v_add_u32_e32 v114, v124, v137
	v_add_u32_e32 v116, v124, v138
	v_add_u32_e32 v122, v124, v140
	v_add_u32_e32 v124, v124, v142
	ds_read_b64 v[70:71], v70
	ds_read_b64 v[72:73], v72
	ds_read_b64 v[74:75], v74
	ds_read_b64 v[76:77], v76
	ds_read_b64 v[82:83], v82
	ds_read_b64 v[84:85], v84
	ds_read_b64 v[90:91], v90
	ds_read_b64 v[92:93], v92
	ds_read_b64 v[98:99], v98
	ds_read_b64 v[100:101], v100
	ds_read_b64 v[106:107], v106
	ds_read_b64 v[108:109], v108
	ds_read_b64 v[114:115], v114
	ds_read_b64 v[116:117], v116
	ds_read_b64 v[122:123], v122
	ds_read_b64 v[124:125], v124
	s_setprio 1
	v_mfma_f32_16x16x32_bf16 v[162:165], v[78:81], v[6:9], 0
	v_mfma_f32_16x16x32_bf16 v[78:81], v[78:81], v[22:25], 0
	s_waitcnt lgkmcnt(14)
	v_mfma_f32_16x16x32_bf16 v[162:165], v[86:89], v[10:13], v[162:165]
	v_mfma_f32_16x16x32_bf16 v[78:81], v[86:89], v[26:29], v[78:81]
	v_mfma_f32_16x16x32_bf16 v[86:89], v[94:97], v[14:17], v[162:165]
	v_mfma_f32_16x16x32_bf16 v[78:81], v[94:97], v[30:33], v[78:81]
	v_mfma_f32_16x16x32_bf16 v[86:89], v[102:105], v[18:21], v[86:89]
	v_mfma_f32_16x16x32_bf16 v[78:81], v[102:105], v[34:37], v[78:81]
	v_mfma_f32_16x16x32_bf16 v[86:89], v[110:113], v[38:41], v[86:89]
	v_mfma_f32_16x16x32_bf16 v[78:81], v[110:113], v[54:57], v[78:81]
	v_mfma_f32_16x16x32_bf16 v[86:89], v[118:121], v[42:45], v[86:89]
	v_mfma_f32_16x16x32_bf16 v[78:81], v[118:121], v[58:61], v[78:81]
	v_mfma_f32_16x16x32_bf16 v[86:89], v[126:129], v[46:49], v[86:89]
	v_mfma_f32_16x16x32_bf16 v[78:81], v[126:129], v[62:65], v[78:81]
	v_mfma_f32_16x16x32_bf16 v[86:89], v[130:133], v[50:53], v[86:89]
	v_mfma_f32_16x16x32_bf16 v[78:81], v[130:133], v[66:69], v[78:81]
	s_setprio 0
	s_nop 5
	v_mul_f32_e32 v86, v5, v86
	v_mul_f32_e32 v87, v5, v87
	v_mul_f32_e32 v78, v136, v78
	v_cvt_pk_bf16_f32 v158, v86, v87
	v_mul_f32_e32 v86, v5, v88
	v_mul_f32_e32 v87, v5, v89
	v_cvt_pk_bf16_f32 v159, v86, v87
	v_mul_f32_e32 v79, v136, v79
	v_cvt_pk_bf16_f32 v162, v78, v79
	v_mul_f32_e32 v78, v136, v80
	v_add_u32_e32 v132, 0x1c800, v146
	v_mul_f32_e32 v79, v136, v81
	v_cvt_pk_bf16_f32 v163, v78, v79
	global_store_dwordx4 v[2:3], v[156:159], off offset:384 sc1
	global_store_dwordx4 v[134:135], v[160:163], off offset:384 sc1
	v_add_u32_e32 v78, v132, v149
	v_add_u32_e32 v80, v132, v151
	v_add_u32_e32 v86, v132, v153
	v_add_u32_e32 v88, v132, v154
	v_add_u32_e32 v94, v132, v143
	v_add_u32_e32 v96, v132, v147
	v_add_u32_e32 v102, v132, v150
	v_add_u32_e32 v104, v132, v152
	v_add_u32_e32 v110, v132, v139
	v_add_u32_e32 v112, v132, v141
	v_add_u32_e32 v118, v132, v145
	v_add_u32_e32 v120, v132, v148
	v_add_u32_e32 v126, v132, v137
	v_add_u32_e32 v128, v132, v138
	v_add_u32_e32 v130, v132, v140
	v_add_u32_e32 v132, v132, v142
	ds_read_b64 v[78:79], v78
	ds_read_b64 v[80:81], v80
	ds_read_b64 v[86:87], v86
	ds_read_b64 v[88:89], v88
	ds_read_b64 v[94:95], v94
	ds_read_b64 v[96:97], v96
	ds_read_b64 v[102:103], v102
	ds_read_b64 v[104:105], v104
	ds_read_b64 v[110:111], v110
	ds_read_b64 v[112:113], v112
	ds_read_b64 v[118:119], v118
	ds_read_b64 v[120:121], v120
	ds_read_b64 v[126:127], v126
	ds_read_b64 v[128:129], v128
	ds_read_b64 v[130:131], v130
	ds_read_b64 v[132:133], v132
	s_setprio 1
	v_mfma_f32_16x16x32_bf16 v[138:141], v[70:73], v[6:9], 0
	v_mfma_f32_16x16x32_bf16 v[70:73], v[70:73], v[22:25], 0
	s_waitcnt lgkmcnt(14)
	v_mfma_f32_16x16x32_bf16 v[138:141], v[74:77], v[10:13], v[138:141]
	v_mfma_f32_16x16x32_bf16 v[70:73], v[74:77], v[26:29], v[70:73]
	v_mfma_f32_16x16x32_bf16 v[74:77], v[82:85], v[14:17], v[138:141]
	v_mfma_f32_16x16x32_bf16 v[70:73], v[82:85], v[30:33], v[70:73]
	v_mfma_f32_16x16x32_bf16 v[74:77], v[90:93], v[18:21], v[74:77]
	v_mfma_f32_16x16x32_bf16 v[70:73], v[90:93], v[34:37], v[70:73]
	v_mfma_f32_16x16x32_bf16 v[74:77], v[98:101], v[38:41], v[74:77]
	v_mfma_f32_16x16x32_bf16 v[70:73], v[98:101], v[54:57], v[70:73]
	v_mfma_f32_16x16x32_bf16 v[74:77], v[106:109], v[42:45], v[74:77]
	v_mfma_f32_16x16x32_bf16 v[70:73], v[106:109], v[58:61], v[70:73]
	v_mfma_f32_16x16x32_bf16 v[74:77], v[114:117], v[46:49], v[74:77]
	v_mfma_f32_16x16x32_bf16 v[70:73], v[114:117], v[62:65], v[70:73]
	v_mfma_f32_16x16x32_bf16 v[74:77], v[122:125], v[50:53], v[74:77]
	v_mfma_f32_16x16x32_bf16 v[70:73], v[122:125], v[66:69], v[70:73]
	s_setprio 0
	s_nop 5
	v_mul_f32_e32 v74, v5, v74
	v_mul_f32_e32 v75, v5, v75
	v_mul_f32_e32 v70, v136, v70
	v_mul_f32_e32 v71, v136, v71
	v_cvt_pk_bf16_f32 v74, v74, v75
	v_mul_f32_e32 v75, v5, v76
	v_cvt_pk_bf16_f32 v70, v70, v71
	v_mul_f32_e32 v71, v136, v72
	v_mul_f32_e32 v76, v5, v77
	v_cvt_pk_bf16_f32 v75, v75, v76
	v_mul_f32_e32 v72, v136, v73
	v_cvt_pk_bf16_f32 v71, v71, v72
	s_setprio 1
	v_mfma_f32_16x16x32_bf16 v[6:9], v[78:81], v[6:9], 0
	v_mfma_f32_16x16x32_bf16 v[22:25], v[78:81], v[22:25], 0
	s_waitcnt lgkmcnt(12)
	v_mfma_f32_16x16x32_bf16 v[6:9], v[86:89], v[10:13], v[6:9]
	v_mfma_f32_16x16x32_bf16 v[10:13], v[86:89], v[26:29], v[22:25]
	s_waitcnt lgkmcnt(10)
	v_mfma_f32_16x16x32_bf16 v[6:9], v[94:97], v[14:17], v[6:9]
	v_mfma_f32_16x16x32_bf16 v[10:13], v[94:97], v[30:33], v[10:13]
	s_waitcnt lgkmcnt(8)
	v_mfma_f32_16x16x32_bf16 v[6:9], v[102:105], v[18:21], v[6:9]
	v_mfma_f32_16x16x32_bf16 v[10:13], v[102:105], v[34:37], v[10:13]
	s_waitcnt lgkmcnt(6)
	v_mfma_f32_16x16x32_bf16 v[6:9], v[110:113], v[38:41], v[6:9]
	v_mfma_f32_16x16x32_bf16 v[10:13], v[110:113], v[54:57], v[10:13]
	s_waitcnt lgkmcnt(4)
	v_mfma_f32_16x16x32_bf16 v[6:9], v[118:121], v[42:45], v[6:9]
	v_mfma_f32_16x16x32_bf16 v[10:13], v[118:121], v[58:61], v[10:13]
	s_waitcnt lgkmcnt(2)
	v_mfma_f32_16x16x32_bf16 v[6:9], v[126:129], v[46:49], v[6:9]
	v_mfma_f32_16x16x32_bf16 v[10:13], v[126:129], v[62:65], v[10:13]
	s_waitcnt lgkmcnt(0)
	v_mfma_f32_16x16x32_bf16 v[6:9], v[130:133], v[50:53], v[6:9]
	v_mfma_f32_16x16x32_bf16 v[10:13], v[130:133], v[66:69], v[10:13]
	s_setprio 0
	s_nop 5
	v_mul_f32_e32 v6, v5, v6
	v_mul_f32_e32 v7, v5, v7
	v_cvt_pk_bf16_f32 v76, v6, v7
	v_mul_f32_e32 v6, v5, v8
	v_mul_f32_e32 v5, v5, v9
	v_cvt_pk_bf16_f32 v77, v6, v5
	v_mul_f32_e32 v5, v136, v10
	v_mul_f32_e32 v6, v136, v11
	v_cvt_pk_bf16_f32 v72, v5, v6
	v_mul_f32_e32 v5, v136, v12
	v_mul_f32_e32 v6, v136, v13
	v_cvt_pk_bf16_f32 v73, v5, v6
	global_store_dwordx4 v[2:3], v[74:77], off offset:448 sc1
	global_store_dwordx4 v[134:135], v[70:73], off offset:448 sc1
	s_barrier
